# gMLP LayerNorm wave sums: bpermute butterflies replaced by DPP adds + permlane16/32 swaps (bit-identical pairing)
# speedup vs baseline: 1.0157x; 1.0081x over previous
; __device__ __forceinline__ float wave_sum(float v) {
; #pragma unroll
;     for (int o = 1; o < 64; o <<= 1) v += __shfl_xor(v, o);
;     return v;
; }
; __device__ __forceinline__ void gmlp_item(Frame& F, const Args& a, int l, int chunk, int g, const bf16* P, bf16* ACTA) {
;     ...
;         for (int i = 0; i < 8; ++i) {
;             const int s = w * 16 + i0 + i; f32x4 x0 = xa[i], x1 = xb[i];
; #pragma unroll
;             for (int j = 0; j < 4; ++j) { x0[j] = gelu_tanh(x0[j]); x1[j] = gelu_tanh(x1[j]); }
;             const float mean = wave_sum((x0[0] + x0[1]) + (x0[2] + x0[3]) + (x1[0] + x1[1]) + (x1[2] + x1[3])) * (1.f / 512.f);
;             x0 -= mean; x1 -= mean;
;             const float var = wave_sum((x0[0] * x0[0] + x0[1] * x0[1]) + (x0[2] * x0[2] + x0[3] * x0[3]) + (x1[0] * x1[0] + x1[1] * x1[1]) + (x1[2] * x1[2] + x1[3] * x1[3])) * (1.f / 512.f);
;             const float rstd = 1.0f / sqrtf(var + 1e-5f);
.LBB0_545:
	s_or_b64 exec, exec, s[2:3]
	v_lshlrev_b32_e32 v42, 16, v40
	v_lshlrev_b32_e32 v44, 16, v41
	v_and_b32_e32 v45, 0xffff0000, v41
	v_mul_f32_e32 v41, 0x3d372713, v42
	v_mul_f32_e32 v41, v41, v42
	v_mov_b32_e32 v46, v42
	v_fmac_f32_e32 v46, v41, v46
	v_mul_f32_e32 v41, 0x3f4c422a, v46
	v_mul_f32_e32 v41, 0x4038aa3b, v41
	v_exp_f32_e32 v46, v41
	v_and_b32_e32 v43, 0xffff0000, v40
	v_lshlrev_b32_e32 v40, 16, v38
	v_lshlrev_b32_e32 v48, 16, v39
	v_and_b32_e32 v49, 0xffff0000, v39
	v_mul_f32_e32 v39, 0x3d372713, v40
	v_and_b32_e32 v41, 0xffff0000, v38
	v_add_f32_e32 v38, 1.0, v46
	v_mul_f32_e32 v39, v39, v40
	v_mov_b32_e32 v46, v40
	v_fmac_f32_e32 v46, v39, v46
	v_mul_f32_e32 v39, 0x3d372713, v43
	v_mul_f32_e32 v39, v39, v43
	v_mov_b32_e32 v62, v43
	v_fmac_f32_e32 v62, v39, v62
	v_mul_f32_e32 v39, 0x3f4c422a, v62
	v_mul_f32_e32 v62, 0x3d372713, v41
	v_mul_f32_e32 v62, v62, v41
	v_mov_b32_e32 v63, v41
	v_mul_f32_e32 v39, 0x4038aa3b, v39
	v_mul_f32_e32 v46, 0x3f4c422a, v46
	v_fmac_f32_e32 v63, v62, v63
	v_exp_f32_e32 v39, v39
	v_mul_f32_e32 v46, 0x4038aa3b, v46
	v_mul_f32_e32 v62, 0x3f4c422a, v63
	v_exp_f32_e32 v46, v46
	v_mul_f32_e32 v62, 0x4038aa3b, v62
	v_exp_f32_e32 v63, v62
	v_add_f32_e32 v39, 1.0, v39
	v_rcp_f32_e32 v38, v38
	v_rcp_f32_e32 v39, v39
	v_add_f32_e32 v46, 1.0, v46
	v_rcp_f32_e32 v62, v46
	v_add_f32_e32 v46, 1.0, v63
	v_rcp_f32_e32 v63, v46
	v_pk_fma_f32 v[38:39], v[38:39], 2.0, 1.0 op_sel_hi:[1,0,0] neg_lo:[1,0,0] neg_hi:[1,0,0]
	v_pk_mul_f32 v[42:43], v[42:43], 0.5 op_sel_hi:[1,0]
	v_pk_add_f32 v[38:39], v[38:39], 1.0 op_sel_hi:[1,0]
	v_mul_f32_e32 v46, 0x3d372713, v44
	v_pk_mul_f32 v[38:39], v[42:43], v[38:39]
	v_pk_fma_f32 v[42:43], v[62:63], 2.0, 1.0 op_sel_hi:[1,0,0] neg_lo:[1,0,0] neg_hi:[1,0,0]
	v_mul_f32_e32 v46, v46, v44
	v_mov_b32_e32 v62, v44
	v_fmac_f32_e32 v62, v46, v62
	v_mul_f32_e32 v46, 0x3f4c422a, v62
	v_mul_f32_e32 v46, 0x4038aa3b, v46
	v_exp_f32_e32 v46, v46
	v_pk_mul_f32 v[40:41], v[40:41], 0.5 op_sel_hi:[1,0]
	v_pk_add_f32 v[42:43], v[42:43], 1.0 op_sel_hi:[1,0]
	v_mov_b32_e32 v62, v45
	v_pk_mul_f32 v[40:41], v[40:41], v[42:43]
	v_mul_f32_e32 v43, 0x3d372713, v48
	v_add_f32_e32 v42, 1.0, v46
	v_mul_f32_e32 v43, v43, v48
	v_mov_b32_e32 v46, v48
	v_fmac_f32_e32 v46, v43, v46
	v_mul_f32_e32 v43, 0x3d372713, v45
	v_mul_f32_e32 v43, v43, v45
	v_fmac_f32_e32 v62, v43, v62
	v_mul_f32_e32 v43, 0x3f4c422a, v62
	v_mul_f32_e32 v62, 0x3d372713, v49
	v_mul_f32_e32 v62, v62, v49
	v_mov_b32_e32 v63, v49
	v_mul_f32_e32 v43, 0x4038aa3b, v43
	v_mul_f32_e32 v46, 0x3f4c422a, v46
	v_fmac_f32_e32 v63, v62, v63
	v_exp_f32_e32 v43, v43
	v_mul_f32_e32 v46, 0x4038aa3b, v46
	v_mul_f32_e32 v62, 0x3f4c422a, v63
	v_exp_f32_e32 v46, v46
	v_mul_f32_e32 v62, 0x4038aa3b, v62
	v_exp_f32_e32 v63, v62
	v_add_f32_e32 v43, 1.0, v43
	v_rcp_f32_e32 v42, v42
	v_rcp_f32_e32 v43, v43
	v_add_f32_e32 v46, 1.0, v46
	v_rcp_f32_e32 v62, v46
	v_add_f32_e32 v46, 1.0, v63
	v_rcp_f32_e32 v63, v46
	v_pk_fma_f32 v[42:43], v[42:43], 2.0, 1.0 op_sel_hi:[1,0,0] neg_lo:[1,0,0] neg_hi:[1,0,0]
	v_pk_mul_f32 v[44:45], v[44:45], 0.5 op_sel_hi:[1,0]
	v_pk_add_f32 v[42:43], v[42:43], 1.0 op_sel_hi:[1,0]
	v_pk_mul_f32 v[48:49], v[48:49], 0.5 op_sel_hi:[1,0]
	v_pk_mul_f32 v[42:43], v[44:45], v[42:43]
	v_pk_fma_f32 v[44:45], v[62:63], 2.0, 1.0 op_sel_hi:[1,0,0] neg_lo:[1,0,0] neg_hi:[1,0,0]
	v_mov_b32_e32 v62, v39
	v_pk_add_f32 v[44:45], v[44:45], 1.0 op_sel_hi:[1,0]
	v_mov_b32_e32 v63, v43
	v_pk_mul_f32 v[44:45], v[48:49], v[44:45]
	v_mov_b32_e32 v48, v38
	v_mov_b32_e32 v49, v42
	v_pk_add_f32 v[48:49], v[48:49], v[62:63]
	v_mov_b32_e32 v62, v44
	v_mov_b32_e32 v63, v40
	s_waitcnt lgkmcnt(0)
	v_mov_b32_e32 v64, v45
	v_mov_b32_e32 v65, v41
	v_pk_add_f32 v[62:63], v[62:63], v[64:65]
	v_add_f32_e32 v46, v48, v49
	v_add_f32_e32 v46, v63, v46
	v_add_f32_e32 v46, v62, v46
	s_waitcnt lgkmcnt(0)
	s_nop 1
	v_add_f32_dpp v46, v46, v46 quad_perm:[1,0,3,2] row_mask:0xf bank_mask:0xf
	s_nop 1
	v_add_f32_dpp v46, v46, v46 quad_perm:[2,3,0,1] row_mask:0xf bank_mask:0xf
	s_nop 1
	v_add_f32_dpp v46, v46, v46 row_half_mirror row_mask:0xf bank_mask:0xf
	s_nop 1
	v_add_f32_dpp v46, v46, v46 row_mirror row_mask:0xf bank_mask:0xf
	v_mov_b32_e32 v48, v46
	s_nop 1
	v_permlane16_swap_b32 v48, v46
	v_add_f32_e32 v46, v46, v48
	v_mov_b32_e32 v48, v46
	s_nop 1
	v_permlane32_swap_b32 v48, v46
	v_add_f32_e32 v46, v46, v48
	v_fmamk_f32 v43, v46, 0xbb000000, v43
	v_fmamk_f32 v39, v46, 0xbb000000, v39
	v_fmac_f32_e32 v42, 0xbb000000, v46
	v_fmac_f32_e32 v38, 0xbb000000, v46
	v_fmamk_f32 v45, v46, 0xbb000000, v45
	v_fmac_f32_e32 v44, 0xbb000000, v46
	v_fmamk_f32 v41, v46, 0xbb000000, v41
	v_fmac_f32_e32 v40, 0xbb000000, v46
	v_mul_f32_e32 v46, v39, v39
	v_mul_f32_e32 v48, v43, v43
	v_fmac_f32_e32 v46, v38, v38
	v_fmac_f32_e32 v48, v42, v42
	v_add_f32_e32 v46, v46, v48
	v_mul_f32_e32 v48, v41, v41
	v_fmac_f32_e32 v48, v40, v40
	v_add_f32_e32 v46, v48, v46
	v_mul_f32_e32 v48, v45, v45
	v_fmac_f32_e32 v48, v44, v44
	v_add_f32_e32 v46, v48, v46
	s_waitcnt lgkmcnt(0)
	s_nop 1
	v_add_f32_dpp v46, v46, v46 quad_perm:[1,0,3,2] row_mask:0xf bank_mask:0xf
	s_nop 1
	v_add_f32_dpp v46, v46, v46 quad_perm:[2,3,0,1] row_mask:0xf bank_mask:0xf
	s_nop 1
	v_add_f32_dpp v46, v46, v46 row_half_mirror row_mask:0xf bank_mask:0xf
	s_nop 1
	v_add_f32_dpp v46, v46, v46 row_mirror row_mask:0xf bank_mask:0xf
	v_mov_b32_e32 v48, v46
	s_nop 1
	v_permlane16_swap_b32 v48, v46
	v_add_f32_e32 v46, v46, v48
	ds_bpermute_b32 v48, v59, v46
	s_and_saveexec_b64 s[2:3], s[38:39]
	s_cbranch_execz .LBB0_547
; __device__ __forceinline__ unsigned f2bf(float f) { unsigned u = __builtin_bit_cast(unsigned, f); return (u + 0x7fffu + ((u >> 16) & 1u)) >> 16; }
; __device__ __forceinline__ void gmlp_item(Frame& F, const Args& a, int l, int chunk, int g, const bf16* P, bf16* ACTA) {
;     ...
;             for (int j = 0; j < 4; ++j) { x0[j] = gelu_tanh(x0[j]); x1[j] = gelu_tanh(x1[j]); }
;             const float mean = wave_sum((x0[0] + x0[1]) + (x0[2] + x0[3]) + (x1[0] + x1[1]) + (x1[2] + x1[3])) * (1.f / 512.f);
;     ...
;             const float rstd = 1.0f / sqrtf(var + 1e-5f);
;             const f32x4 xm = myj ? x1 : x0;
;             if ((lane >> 5) == (g & 1)) {
;                 const int cl = 4 * (lane - mylo);
; #pragma unroll
;                 for (int j = 0; j < 4; ++j) Vt[(cl + j) * 136 + s] = (bf16)f2bf(xm[j] * rstd * lgv[j] + lbv[j]);
;             }
	v_cndmask_b32_e64 v38, v40, v38, s[0:1]
	s_waitcnt lgkmcnt(0)
	v_add_f32_e32 v40, v46, v48
	v_fmamk_f32 v40, v40, 0x3b000000, v215
	v_cndmask_b32_e64 v39, v41, v39, s[0:1]
	v_cmp_gt_f32_e32 vcc, s67, v40
	v_mul_f32_e32 v41, 0x4f800000, v40
	v_cndmask_b32_e64 v42, v44, v42, s[0:1]
	v_cndmask_b32_e32 v40, v40, v41, vcc
	v_sqrt_f32_e32 v41, v40
	v_cndmask_b32_e64 v43, v45, v43, s[0:1]
	v_add_u32_e32 v44, -1, v41
	v_fma_f32 v45, -v44, v41, v40
	v_cmp_ge_f32_e64 s[4:5], 0, v45
	v_add_u32_e32 v45, 1, v41
	s_nop 0
	v_cndmask_b32_e64 v44, v41, v44, s[4:5]
	v_fma_f32 v41, -v45, v41, v40
	v_cmp_lt_f32_e64 s[4:5], 0, v41
	s_nop 1
	v_cndmask_b32_e64 v41, v44, v45, s[4:5]
	v_mul_f32_e32 v44, 0x37800000, v41
	v_cndmask_b32_e32 v41, v41, v44, vcc
	v_cmp_class_f32_e32 vcc, v40, v213
	s_nop 1
	v_cndmask_b32_e32 v40, v41, v40, vcc
	v_div_scale_f32 v41, s[4:5], v40, v40, 1.0
	v_rcp_f32_e32 v44, v41
	s_nop 0
	v_fma_f32 v45, -v41, v44, 1.0
	v_fmac_f32_e32 v44, v45, v44
	v_div_scale_f32 v45, vcc, 1.0, v40, 1.0
	v_mul_f32_e32 v46, v45, v44
	v_fma_f32 v48, -v41, v46, v45
	v_fmac_f32_e32 v46, v48, v44
	v_fma_f32 v41, -v41, v46, v45
	v_div_fmas_f32 v41, v41, v44, v46
	v_div_fixup_f32 v40, v41, v40, 1.0
	v_mul_f32_e32 v38, v38, v40
	v_fma_f32 v38, v2, v38, v6
	v_bfe_u32 v41, v38, 16, 1
	v_add3_u32 v38, v38, v41, s7
	ds_write_b16_d16_hi v47, v38 offset:2
	v_mul_f32_e32 v38, v39, v40
	v_fma_f32 v38, v3, v38, v7
	v_bfe_u32 v39, v38, 16, 1
	v_add3_u32 v38, v38, v39, s7
	ds_write_b16_d16_hi v47, v38 offset:274
	v_mul_f32_e32 v38, v42, v40
	v_fma_f32 v38, v4, v38, v8
	v_bfe_u32 v39, v38, 16, 1
	v_add3_u32 v38, v38, v39, s7
	ds_write_b16_d16_hi v47, v38 offset:546
	v_mul_f32_e32 v38, v43, v40
	v_fma_f32 v38, v5, v38, v9
	v_bfe_u32 v39, v38, 16, 1
	v_add3_u32 v38, v38, v39, s7
	ds_write_b16_d16_hi v47, v38 offset:818
.LBB0_547:
	s_or_b64 exec, exec, s[2:3]
	v_lshlrev_b32_e32 v38, 16, v36
	v_lshlrev_b32_e32 v40, 16, v37
	v_and_b32_e32 v41, 0xffff0000, v37
	v_mul_f32_e32 v37, 0x3d372713, v38
	v_mul_f32_e32 v37, v37, v38
	v_mov_b32_e32 v42, v38
	v_fmac_f32_e32 v42, v37, v42
	v_mul_f32_e32 v37, 0x3f4c422a, v42
	v_mul_f32_e32 v37, 0x4038aa3b, v37
	v_exp_f32_e32 v44, v37
	v_and_b32_e32 v39, 0xffff0000, v36
	v_lshlrev_b32_e32 v36, 16, v32
	v_lshlrev_b32_e32 v42, 16, v33
	v_and_b32_e32 v43, 0xffff0000, v33
	v_mul_f32_e32 v33, 0x3d372713, v36
	v_and_b32_e32 v37, 0xffff0000, v32
	v_add_f32_e32 v32, 1.0, v44
	v_mul_f32_e32 v33, v33, v36
	v_mov_b32_e32 v44, v36
	v_fmac_f32_e32 v44, v33, v44
	v_mul_f32_e32 v33, 0x3d372713, v39
	v_mul_f32_e32 v33, v33, v39
	v_mov_b32_e32 v45, v39
	v_fmac_f32_e32 v45, v33, v45
	v_mul_f32_e32 v33, 0x3f4c422a, v45
	v_mul_f32_e32 v45, 0x3d372713, v37
	v_mul_f32_e32 v45, v45, v37
	v_mov_b32_e32 v46, v37
	v_mul_f32_e32 v33, 0x4038aa3b, v33
	v_fmac_f32_e32 v46, v45, v46
	v_exp_f32_e32 v33, v33
	v_mul_f32_e32 v44, 0x3f4c422a, v44
	v_mul_f32_e32 v45, 0x3f4c422a, v46
	v_mul_f32_e32 v44, 0x4038aa3b, v44
	v_mul_f32_e32 v45, 0x4038aa3b, v45
	v_exp_f32_e32 v44, v44
	v_exp_f32_e32 v45, v45
	v_add_f32_e32 v33, 1.0, v33
	v_rcp_f32_e32 v32, v32
	v_rcp_f32_e32 v33, v33
	v_add_f32_e32 v44, 1.0, v44
	v_add_f32_e32 v45, 1.0, v45
	v_rcp_f32_e32 v44, v44
	v_rcp_f32_e32 v45, v45
	v_pk_fma_f32 v[32:33], v[32:33], 2.0, 1.0 op_sel_hi:[1,0,0] neg_lo:[1,0,0] neg_hi:[1,0,0]
	v_pk_mul_f32 v[38:39], v[38:39], 0.5 op_sel_hi:[1,0]
	v_pk_add_f32 v[32:33], v[32:33], 1.0 op_sel_hi:[1,0]
	v_pk_mul_f32 v[36:37], v[36:37], 0.5 op_sel_hi:[1,0]
	v_pk_mul_f32 v[32:33], v[38:39], v[32:33]
	v_pk_fma_f32 v[38:39], v[44:45], 2.0, 1.0 op_sel_hi:[1,0,0] neg_lo:[1,0,0] neg_hi:[1,0,0]
	v_mul_f32_e32 v44, 0x3d372713, v40
	v_mul_f32_e32 v44, v44, v40
	v_mov_b32_e32 v45, v40
	v_fmac_f32_e32 v45, v44, v45
	v_mul_f32_e32 v44, 0x3f4c422a, v45
	v_mul_f32_e32 v44, 0x4038aa3b, v44
	v_exp_f32_e32 v44, v44
	v_pk_add_f32 v[38:39], v[38:39], 1.0 op_sel_hi:[1,0]
	v_mov_b32_e32 v45, v41
	v_pk_mul_f32 v[36:37], v[36:37], v[38:39]
	v_mul_f32_e32 v39, 0x3d372713, v42
	v_add_f32_e32 v38, 1.0, v44
	v_mul_f32_e32 v39, v39, v42
	v_mov_b32_e32 v44, v42
	v_fmac_f32_e32 v44, v39, v44
	v_mul_f32_e32 v39, 0x3d372713, v41
	v_mul_f32_e32 v39, v39, v41
	v_fmac_f32_e32 v45, v39, v45
	v_mul_f32_e32 v39, 0x3f4c422a, v45
	v_mul_f32_e32 v45, 0x3d372713, v43
	v_mul_f32_e32 v45, v45, v43
	v_mov_b32_e32 v46, v43
	v_mul_f32_e32 v39, 0x4038aa3b, v39
	v_fmac_f32_e32 v46, v45, v46
	v_exp_f32_e32 v39, v39
	v_mul_f32_e32 v44, 0x3f4c422a, v44
	v_mul_f32_e32 v45, 0x3f4c422a, v46
	v_mul_f32_e32 v44, 0x4038aa3b, v44
	v_mul_f32_e32 v45, 0x4038aa3b, v45
	v_exp_f32_e32 v44, v44
	v_exp_f32_e32 v45, v45
	v_add_f32_e32 v39, 1.0, v39
	v_rcp_f32_e32 v38, v38
	v_rcp_f32_e32 v39, v39
	v_add_f32_e32 v44, 1.0, v44
	v_add_f32_e32 v45, 1.0, v45
	v_rcp_f32_e32 v44, v44
	v_rcp_f32_e32 v45, v45
	v_pk_fma_f32 v[38:39], v[38:39], 2.0, 1.0 op_sel_hi:[1,0,0] neg_lo:[1,0,0] neg_hi:[1,0,0]
	v_pk_mul_f32 v[40:41], v[40:41], 0.5 op_sel_hi:[1,0]
	v_pk_add_f32 v[38:39], v[38:39], 1.0 op_sel_hi:[1,0]
	v_pk_mul_f32 v[42:43], v[42:43], 0.5 op_sel_hi:[1,0]
	v_pk_mul_f32 v[38:39], v[40:41], v[38:39]
	v_pk_fma_f32 v[40:41], v[44:45], 2.0, 1.0 op_sel_hi:[1,0,0] neg_lo:[1,0,0] neg_hi:[1,0,0]
	v_mov_b32_e32 v44, v33
	v_pk_add_f32 v[40:41], v[40:41], 1.0 op_sel_hi:[1,0]
	v_mov_b32_e32 v45, v39
	v_pk_mul_f32 v[40:41], v[42:43], v[40:41]
	v_mov_b32_e32 v42, v32
	v_mov_b32_e32 v43, v38
	v_pk_add_f32 v[42:43], v[42:43], v[44:45]
	v_mov_b32_e32 v44, v40
	v_mov_b32_e32 v45, v36
	s_waitcnt lgkmcnt(0)
	v_mov_b32_e32 v48, v41
	v_mov_b32_e32 v49, v37
	v_pk_add_f32 v[44:45], v[44:45], v[48:49]
	v_add_f32_e32 v42, v42, v43
	v_add_f32_e32 v42, v45, v42
	v_add_f32_e32 v42, v44, v42
	s_waitcnt lgkmcnt(0)
; __device__ __forceinline__ unsigned f2bf(float f) { unsigned u = __builtin_bit_cast(unsigned, f); return (u + 0x7fffu + ((u >> 16) & 1u)) >> 16; }
; __device__ __forceinline__ void gmlp_item(Frame& F, const Args& a, int l, int chunk, int g, const bf16* P, bf16* ACTA) {
;     ...
;             for (int j = 0; j < 4; ++j) { x0[j] = gelu_tanh(x0[j]); x1[j] = gelu_tanh(x1[j]); }
;             const float mean = wave_sum((x0[0] + x0[1]) + (x0[2] + x0[3]) + (x1[0] + x1[1]) + (x1[2] + x1[3])) * (1.f / 512.f);
;             x0 -= mean; x1 -= mean;
;             const float var = wave_sum((x0[0] * x0[0] + x0[1] * x0[1]) + (x0[2] * x0[2] + x0[3] * x0[3]) + (x1[0] * x1[0] + x1[1] * x1[1]) + (x1[2] * x1[2] + x1[3] * x1[3])) * (1.f / 512.f);
;             const float rstd = 1.0f / sqrtf(var + 1e-5f);
;             const f32x4 xm = myj ? x1 : x0;
;             if ((lane >> 5) == (g & 1)) {
;                 const int cl = 4 * (lane - mylo);
; #pragma unroll
;                 for (int j = 0; j < 4; ++j) Vt[(cl + j) * 136 + s] = (bf16)f2bf(xm[j] * rstd * lgv[j] + lbv[j]);
;             }
	s_nop 1
	v_add_f32_dpp v42, v42, v42 quad_perm:[1,0,3,2] row_mask:0xf bank_mask:0xf
	s_nop 1
	v_add_f32_dpp v42, v42, v42 quad_perm:[2,3,0,1] row_mask:0xf bank_mask:0xf
	s_nop 1
	v_add_f32_dpp v42, v42, v42 row_half_mirror row_mask:0xf bank_mask:0xf
	s_nop 1
	v_add_f32_dpp v42, v42, v42 row_mirror row_mask:0xf bank_mask:0xf
	v_mov_b32_e32 v43, v42
	s_nop 1
	v_permlane16_swap_b32 v43, v42
	v_add_f32_e32 v42, v42, v43
	v_mov_b32_e32 v43, v42
	s_nop 1
	v_permlane32_swap_b32 v43, v42
	v_add_f32_e32 v42, v42, v43
	v_fmamk_f32 v39, v42, 0xbb000000, v39
	v_fmamk_f32 v33, v42, 0xbb000000, v33
	v_fmac_f32_e32 v38, 0xbb000000, v42
	v_fmac_f32_e32 v32, 0xbb000000, v42
	v_fmamk_f32 v41, v42, 0xbb000000, v41
	v_fmac_f32_e32 v40, 0xbb000000, v42
	v_fmamk_f32 v37, v42, 0xbb000000, v37
	v_fmac_f32_e32 v36, 0xbb000000, v42
	v_mul_f32_e32 v42, v33, v33
	v_mul_f32_e32 v43, v39, v39
	v_fmac_f32_e32 v42, v32, v32
	v_fmac_f32_e32 v43, v38, v38
	v_add_f32_e32 v42, v42, v43
	v_mul_f32_e32 v43, v37, v37
	v_fmac_f32_e32 v43, v36, v36
	v_add_f32_e32 v42, v43, v42
	v_mul_f32_e32 v43, v41, v41
	v_fmac_f32_e32 v43, v40, v40
	v_add_f32_e32 v42, v43, v42
	s_waitcnt lgkmcnt(0)
	s_nop 1
	v_add_f32_dpp v42, v42, v42 quad_perm:[1,0,3,2] row_mask:0xf bank_mask:0xf
	s_nop 1
	v_add_f32_dpp v42, v42, v42 quad_perm:[2,3,0,1] row_mask:0xf bank_mask:0xf
	s_nop 1
	v_add_f32_dpp v42, v42, v42 row_half_mirror row_mask:0xf bank_mask:0xf
	s_nop 1
	v_add_f32_dpp v42, v42, v42 row_mirror row_mask:0xf bank_mask:0xf
	v_mov_b32_e32 v43, v42
	s_nop 1
	v_permlane16_swap_b32 v43, v42
	v_add_f32_e32 v42, v42, v43
	ds_bpermute_b32 v43, v59, v42
	s_and_saveexec_b64 s[2:3], s[38:39]
	s_cbranch_execz .LBB0_549
	v_cndmask_b32_e64 v32, v36, v32, s[0:1]
	s_waitcnt lgkmcnt(0)
	v_add_f32_e32 v36, v42, v43
	v_fmamk_f32 v36, v36, 0x3b000000, v215
	v_cndmask_b32_e64 v33, v37, v33, s[0:1]
	v_cmp_gt_f32_e32 vcc, s67, v36
	v_mul_f32_e32 v37, 0x4f800000, v36
	v_cndmask_b32_e64 v38, v40, v38, s[0:1]
	v_cndmask_b32_e32 v36, v36, v37, vcc
	v_sqrt_f32_e32 v37, v36
	v_cndmask_b32_e64 v39, v41, v39, s[0:1]
	v_add_u32_e32 v40, -1, v37
	v_fma_f32 v41, -v40, v37, v36
	v_cmp_ge_f32_e64 s[4:5], 0, v41
	v_add_u32_e32 v41, 1, v37
	s_nop 0
	v_cndmask_b32_e64 v40, v37, v40, s[4:5]
	v_fma_f32 v37, -v41, v37, v36
	v_cmp_lt_f32_e64 s[4:5], 0, v37
	s_nop 1
	v_cndmask_b32_e64 v37, v40, v41, s[4:5]
	v_mul_f32_e32 v40, 0x37800000, v37
	v_cndmask_b32_e32 v37, v37, v40, vcc
	v_cmp_class_f32_e32 vcc, v36, v213
	s_nop 1
	v_cndmask_b32_e32 v36, v37, v36, vcc
	v_div_scale_f32 v37, s[4:5], v36, v36, 1.0
	v_rcp_f32_e32 v40, v37
	s_nop 0
	v_fma_f32 v41, -v37, v40, 1.0
	v_fmac_f32_e32 v40, v41, v40
	v_div_scale_f32 v41, vcc, 1.0, v36, 1.0
	v_mul_f32_e32 v42, v41, v40
	v_fma_f32 v43, -v37, v42, v41
	v_fmac_f32_e32 v42, v43, v40
	v_fma_f32 v37, -v37, v42, v41
	v_div_fmas_f32 v37, v37, v40, v42
	v_div_fixup_f32 v36, v37, v36, 1.0
	v_mul_f32_e32 v32, v32, v36
	v_fma_f32 v32, v2, v32, v6
	v_bfe_u32 v37, v32, 16, 1
	v_add3_u32 v32, v32, v37, s7
	ds_write_b16_d16_hi v47, v32 offset:4
	v_mul_f32_e32 v32, v33, v36
	v_fma_f32 v32, v3, v32, v7
	v_bfe_u32 v33, v32, 16, 1
	v_add3_u32 v32, v32, v33, s7
	ds_write_b16_d16_hi v47, v32 offset:276
	v_mul_f32_e32 v32, v38, v36
	v_fma_f32 v32, v4, v32, v8
	v_bfe_u32 v33, v32, 16, 1
	v_add3_u32 v32, v32, v33, s7
	ds_write_b16_d16_hi v47, v32 offset:548
	v_mul_f32_e32 v32, v39, v36
	v_fma_f32 v32, v5, v32, v9
	v_bfe_u32 v33, v32, 16, 1
	v_add3_u32 v32, v32, v33, s7
	ds_write_b16_d16_hi v47, v32 offset:820
.LBB0_549:
	s_or_b64 exec, exec, s[2:3]
	v_lshlrev_b32_e32 v32, 16, v30
	v_lshlrev_b32_e32 v36, 16, v31
	v_and_b32_e32 v37, 0xffff0000, v31
	v_mul_f32_e32 v31, 0x3d372713, v32
	v_mul_f32_e32 v31, v31, v32
	v_mov_b32_e32 v38, v32
	v_fmac_f32_e32 v38, v31, v38
	v_mul_f32_e32 v31, 0x3f4c422a, v38
	v_mul_f32_e32 v31, 0x4038aa3b, v31
	v_exp_f32_e32 v40, v31
	v_and_b32_e32 v33, 0xffff0000, v30
	v_lshlrev_b32_e32 v30, 16, v28
	v_lshlrev_b32_e32 v38, 16, v29
	v_and_b32_e32 v39, 0xffff0000, v29
	v_mul_f32_e32 v29, 0x3d372713, v30
	v_and_b32_e32 v31, 0xffff0000, v28
	v_add_f32_e32 v28, 1.0, v40
	v_mul_f32_e32 v29, v29, v30
	v_mov_b32_e32 v40, v30
	v_fmac_f32_e32 v40, v29, v40
	v_mul_f32_e32 v29, 0x3d372713, v33
	v_mul_f32_e32 v29, v29, v33
	v_mov_b32_e32 v41, v33
	v_fmac_f32_e32 v41, v29, v41
	v_mul_f32_e32 v29, 0x3f4c422a, v41
	v_mul_f32_e32 v41, 0x3d372713, v31
	v_mul_f32_e32 v41, v41, v31
	v_mov_b32_e32 v42, v31
	v_mul_f32_e32 v29, 0x4038aa3b, v29
	v_fmac_f32_e32 v42, v41, v42
	v_exp_f32_e32 v29, v29
	v_mul_f32_e32 v40, 0x3f4c422a, v40
	v_mul_f32_e32 v41, 0x3f4c422a, v42
	v_mul_f32_e32 v40, 0x4038aa3b, v40
	v_mul_f32_e32 v41, 0x4038aa3b, v41
	v_exp_f32_e32 v40, v40
	v_exp_f32_e32 v41, v41
	v_add_f32_e32 v29, 1.0, v29
	v_rcp_f32_e32 v28, v28
	v_rcp_f32_e32 v29, v29
	v_add_f32_e32 v40, 1.0, v40
	v_add_f32_e32 v41, 1.0, v41
	v_rcp_f32_e32 v40, v40
	v_rcp_f32_e32 v41, v41
	v_pk_fma_f32 v[28:29], v[28:29], 2.0, 1.0 op_sel_hi:[1,0,0] neg_lo:[1,0,0] neg_hi:[1,0,0]
	v_pk_mul_f32 v[32:33], v[32:33], 0.5 op_sel_hi:[1,0]
	v_pk_add_f32 v[28:29], v[28:29], 1.0 op_sel_hi:[1,0]
	v_pk_mul_f32 v[30:31], v[30:31], 0.5 op_sel_hi:[1,0]
	v_pk_mul_f32 v[28:29], v[32:33], v[28:29]
	v_pk_fma_f32 v[32:33], v[40:41], 2.0, 1.0 op_sel_hi:[1,0,0] neg_lo:[1,0,0] neg_hi:[1,0,0]
	v_mul_f32_e32 v40, 0x3d372713, v36
	v_mul_f32_e32 v40, v40, v36
	v_mov_b32_e32 v41, v36
	v_fmac_f32_e32 v41, v40, v41
	v_mul_f32_e32 v40, 0x3f4c422a, v41
	v_mul_f32_e32 v40, 0x4038aa3b, v40
	v_exp_f32_e32 v40, v40
	v_pk_add_f32 v[32:33], v[32:33], 1.0 op_sel_hi:[1,0]
	v_mov_b32_e32 v41, v37
	v_pk_mul_f32 v[30:31], v[30:31], v[32:33]
	v_mul_f32_e32 v33, 0x3d372713, v38
; __device__ __forceinline__ unsigned f2bf(float f) { unsigned u = __builtin_bit_cast(unsigned, f); return (u + 0x7fffu + ((u >> 16) & 1u)) >> 16; }
; __device__ __forceinline__ void gmlp_item(Frame& F, const Args& a, int l, int chunk, int g, const bf16* P, bf16* ACTA) {
;     ...
;             for (int j = 0; j < 4; ++j) { x0[j] = gelu_tanh(x0[j]); x1[j] = gelu_tanh(x1[j]); }
;             const float mean = wave_sum((x0[0] + x0[1]) + (x0[2] + x0[3]) + (x1[0] + x1[1]) + (x1[2] + x1[3])) * (1.f / 512.f);
;             x0 -= mean; x1 -= mean;
;             const float var = wave_sum((x0[0] * x0[0] + x0[1] * x0[1]) + (x0[2] * x0[2] + x0[3] * x0[3]) + (x1[0] * x1[0] + x1[1] * x1[1]) + (x1[2] * x1[2] + x1[3] * x1[3])) * (1.f / 512.f);
;             const float rstd = 1.0f / sqrtf(var + 1e-5f);
;             const f32x4 xm = myj ? x1 : x0;
;             if ((lane >> 5) == (g & 1)) {
;                 const int cl = 4 * (lane - mylo);
; #pragma unroll
;                 for (int j = 0; j < 4; ++j) Vt[(cl + j) * 136 + s] = (bf16)f2bf(xm[j] * rstd * lgv[j] + lbv[j]);
;             }
	v_add_f32_e32 v32, 1.0, v40
	v_mul_f32_e32 v33, v33, v38
	v_mov_b32_e32 v40, v38
	v_fmac_f32_e32 v40, v33, v40
	v_mul_f32_e32 v33, 0x3d372713, v37
	v_mul_f32_e32 v33, v33, v37
	v_fmac_f32_e32 v41, v33, v41
	v_mul_f32_e32 v33, 0x3f4c422a, v41
	v_mul_f32_e32 v41, 0x3d372713, v39
	v_mul_f32_e32 v41, v41, v39
	v_mov_b32_e32 v42, v39
	v_mul_f32_e32 v33, 0x4038aa3b, v33
	v_fmac_f32_e32 v42, v41, v42
	v_exp_f32_e32 v33, v33
	v_mul_f32_e32 v40, 0x3f4c422a, v40
	v_mul_f32_e32 v41, 0x3f4c422a, v42
	v_mul_f32_e32 v40, 0x4038aa3b, v40
	v_mul_f32_e32 v41, 0x4038aa3b, v41
	v_exp_f32_e32 v40, v40
	v_exp_f32_e32 v41, v41
	v_add_f32_e32 v33, 1.0, v33
	v_rcp_f32_e32 v32, v32
	v_rcp_f32_e32 v33, v33
	v_add_f32_e32 v40, 1.0, v40
	v_add_f32_e32 v41, 1.0, v41
	v_rcp_f32_e32 v40, v40
	v_rcp_f32_e32 v41, v41
	v_pk_fma_f32 v[32:33], v[32:33], 2.0, 1.0 op_sel_hi:[1,0,0] neg_lo:[1,0,0] neg_hi:[1,0,0]
	v_pk_mul_f32 v[36:37], v[36:37], 0.5 op_sel_hi:[1,0]
	v_pk_add_f32 v[32:33], v[32:33], 1.0 op_sel_hi:[1,0]
	v_pk_mul_f32 v[38:39], v[38:39], 0.5 op_sel_hi:[1,0]
	v_pk_mul_f32 v[32:33], v[36:37], v[32:33]
	v_pk_fma_f32 v[36:37], v[40:41], 2.0, 1.0 op_sel_hi:[1,0,0] neg_lo:[1,0,0] neg_hi:[1,0,0]
	v_mov_b32_e32 v40, v29
	v_pk_add_f32 v[36:37], v[36:37], 1.0 op_sel_hi:[1,0]
	v_mov_b32_e32 v41, v33
	v_pk_mul_f32 v[36:37], v[38:39], v[36:37]
	v_mov_b32_e32 v38, v28
	v_mov_b32_e32 v39, v32
	v_pk_add_f32 v[38:39], v[38:39], v[40:41]
	v_mov_b32_e32 v40, v36
	v_mov_b32_e32 v41, v30
	v_mov_b32_e32 v42, v37
	s_waitcnt lgkmcnt(0)
	v_mov_b32_e32 v43, v31
	v_pk_add_f32 v[40:41], v[40:41], v[42:43]
	v_add_f32_e32 v38, v38, v39
	v_add_f32_e32 v38, v41, v38
	v_add_f32_e32 v38, v40, v38
	s_waitcnt lgkmcnt(0)
	s_nop 1
	v_add_f32_dpp v38, v38, v38 quad_perm:[1,0,3,2] row_mask:0xf bank_mask:0xf
	s_nop 1
	v_add_f32_dpp v38, v38, v38 quad_perm:[2,3,0,1] row_mask:0xf bank_mask:0xf
	s_nop 1
	v_add_f32_dpp v38, v38, v38 row_half_mirror row_mask:0xf bank_mask:0xf
	s_nop 1
	v_add_f32_dpp v38, v38, v38 row_mirror row_mask:0xf bank_mask:0xf
	v_mov_b32_e32 v39, v38
	s_nop 1
	v_permlane16_swap_b32 v39, v38
	v_add_f32_e32 v38, v38, v39
	v_mov_b32_e32 v39, v38
	s_nop 1
	v_permlane32_swap_b32 v39, v38
	v_add_f32_e32 v38, v38, v39
	v_fmamk_f32 v33, v38, 0xbb000000, v33
	v_fmamk_f32 v29, v38, 0xbb000000, v29
	v_fmac_f32_e32 v32, 0xbb000000, v38
	v_fmac_f32_e32 v28, 0xbb000000, v38
	v_fmamk_f32 v37, v38, 0xbb000000, v37
	v_fmac_f32_e32 v36, 0xbb000000, v38
	v_fmamk_f32 v31, v38, 0xbb000000, v31
	v_fmac_f32_e32 v30, 0xbb000000, v38
	v_mul_f32_e32 v38, v29, v29
	v_mul_f32_e32 v39, v33, v33
	v_fmac_f32_e32 v38, v28, v28
	v_fmac_f32_e32 v39, v32, v32
	v_add_f32_e32 v38, v38, v39
	v_mul_f32_e32 v39, v31, v31
	v_fmac_f32_e32 v39, v30, v30
	v_add_f32_e32 v38, v39, v38
	v_mul_f32_e32 v39, v37, v37
	v_fmac_f32_e32 v39, v36, v36
	v_add_f32_e32 v38, v39, v38
	s_waitcnt lgkmcnt(0)
	s_nop 1
	v_add_f32_dpp v38, v38, v38 quad_perm:[1,0,3,2] row_mask:0xf bank_mask:0xf
	s_nop 1
	v_add_f32_dpp v38, v38, v38 quad_perm:[2,3,0,1] row_mask:0xf bank_mask:0xf
	s_nop 1
	v_add_f32_dpp v38, v38, v38 row_half_mirror row_mask:0xf bank_mask:0xf
	s_nop 1
	v_add_f32_dpp v38, v38, v38 row_mirror row_mask:0xf bank_mask:0xf
	v_mov_b32_e32 v39, v38
	s_nop 1
	v_permlane16_swap_b32 v39, v38
	v_add_f32_e32 v38, v38, v39
	ds_bpermute_b32 v39, v59, v38
	s_and_saveexec_b64 s[2:3], s[38:39]
	s_cbranch_execz .LBB0_551
	v_cndmask_b32_e64 v28, v30, v28, s[0:1]
	s_waitcnt lgkmcnt(0)
	v_add_f32_e32 v30, v38, v39
	v_fmamk_f32 v30, v30, 0x3b000000, v215
	v_cndmask_b32_e64 v29, v31, v29, s[0:1]
	v_cmp_gt_f32_e32 vcc, s67, v30
	v_mul_f32_e32 v31, 0x4f800000, v30
	v_cndmask_b32_e64 v32, v36, v32, s[0:1]
	v_cndmask_b32_e32 v30, v30, v31, vcc
	v_sqrt_f32_e32 v31, v30
	v_cndmask_b32_e64 v33, v37, v33, s[0:1]
	v_add_u32_e32 v36, -1, v31
	v_fma_f32 v37, -v36, v31, v30
	v_cmp_ge_f32_e64 s[4:5], 0, v37
	v_add_u32_e32 v37, 1, v31
	s_nop 0
	v_cndmask_b32_e64 v36, v31, v36, s[4:5]
	v_fma_f32 v31, -v37, v31, v30
	v_cmp_lt_f32_e64 s[4:5], 0, v31
	s_nop 1
	v_cndmask_b32_e64 v31, v36, v37, s[4:5]
	v_mul_f32_e32 v36, 0x37800000, v31
	v_cndmask_b32_e32 v31, v31, v36, vcc
	v_cmp_class_f32_e32 vcc, v30, v213
	s_nop 1
	v_cndmask_b32_e32 v30, v31, v30, vcc
	v_div_scale_f32 v31, s[4:5], v30, v30, 1.0
	v_rcp_f32_e32 v36, v31
	s_nop 0
	v_fma_f32 v37, -v31, v36, 1.0
	v_fmac_f32_e32 v36, v37, v36
	v_div_scale_f32 v37, vcc, 1.0, v30, 1.0
	v_mul_f32_e32 v38, v37, v36
	v_fma_f32 v39, -v31, v38, v37
	v_fmac_f32_e32 v38, v39, v36
	v_fma_f32 v31, -v31, v38, v37
	v_div_fmas_f32 v31, v31, v36, v38
	v_div_fixup_f32 v30, v31, v30, 1.0
	v_mul_f32_e32 v28, v28, v30
	v_fma_f32 v28, v2, v28, v6
	v_bfe_u32 v31, v28, 16, 1
	v_add3_u32 v28, v28, v31, s7
	ds_write_b16_d16_hi v47, v28 offset:6
	v_mul_f32_e32 v28, v29, v30
	v_fma_f32 v28, v3, v28, v7
	v_bfe_u32 v29, v28, 16, 1
	v_add3_u32 v28, v28, v29, s7
	ds_write_b16_d16_hi v47, v28 offset:278
	v_mul_f32_e32 v28, v32, v30
	v_fma_f32 v28, v4, v28, v8
	v_bfe_u32 v29, v28, 16, 1
	v_add3_u32 v28, v28, v29, s7
	ds_write_b16_d16_hi v47, v28 offset:550
	v_mul_f32_e32 v28, v33, v30
	v_fma_f32 v28, v5, v28, v9
	v_bfe_u32 v29, v28, 16, 1
	v_add3_u32 v28, v28, v29, s7
	ds_write_b16_d16_hi v47, v28 offset:822
; __device__ __forceinline__ float ex2(float x) { return __builtin_amdgcn_exp2f(x); }
; __device__ __forceinline__ float rcpf_(float x) { return __builtin_amdgcn_rcpf(x); }
; __device__ __forceinline__ float gelu_tanh(float x) {
;     const float u = 0.7978845608028654f * (x + 0.044715f * x * x * x);
;     const float t = 1.0f - 2.0f * rcpf_(1.0f + ex2(2.0f * LOG2E * u));
;     return 0.5f * x * (1.0f + t);
; }
; __device__ __forceinline__ void gmlp_item(Frame& F, const Args& a, int l, int chunk, int g, const bf16* P, bf16* ACTA) {
;     ...
;         for (int i = 0; i < 8; ++i) {
;             const int s = w * 16 + i0 + i; f32x4 x0 = xa[i], x1 = xb[i];
; #pragma unroll
;             for (int j = 0; j < 4; ++j) { x0[j] = gelu_tanh(x0[j]); x1[j] = gelu_tanh(x1[j]); }
;             const float mean = wave_sum((x0[0] + x0[1]) + (x0[2] + x0[3]) + (x1[0] + x1[1]) + (x1[2] + x1[3])) * (1.f / 512.f);
;             x0 -= mean; x1 -= mean;
;             const float var = wave_sum((x0[0] * x0[0] + x0[1] * x0[1]) + (x0[2] * x0[2] + x0[3] * x0[3]) + (x1[0] * x1[0] + x1[1] * x1[1]) + (x1[2] * x1[2] + x1[3] * x1[3])) * (1.f / 512.f);
;             const float rstd = 1.0f / sqrtf(var + 1e-5f);
.LBB0_551:
	s_or_b64 exec, exec, s[2:3]
	v_lshlrev_b32_e32 v28, 16, v26
	v_lshlrev_b32_e32 v30, 16, v27
	v_and_b32_e32 v31, 0xffff0000, v27
	v_mul_f32_e32 v27, 0x3d372713, v28
	v_mul_f32_e32 v27, v27, v28
	v_mov_b32_e32 v32, v28
	v_fmac_f32_e32 v32, v27, v32
	v_mul_f32_e32 v27, 0x3f4c422a, v32
	v_mul_f32_e32 v27, 0x4038aa3b, v27
	v_exp_f32_e32 v36, v27
	v_and_b32_e32 v29, 0xffff0000, v26
	v_lshlrev_b32_e32 v26, 16, v24
	v_lshlrev_b32_e32 v32, 16, v25
	v_and_b32_e32 v33, 0xffff0000, v25
	v_mul_f32_e32 v25, 0x3d372713, v26
	v_and_b32_e32 v27, 0xffff0000, v24
	v_add_f32_e32 v24, 1.0, v36
	v_mul_f32_e32 v25, v25, v26
	v_mov_b32_e32 v36, v26
	v_fmac_f32_e32 v36, v25, v36
	v_mul_f32_e32 v25, 0x3d372713, v29
	v_mul_f32_e32 v25, v25, v29
	v_mov_b32_e32 v37, v29
	v_fmac_f32_e32 v37, v25, v37
	v_mul_f32_e32 v25, 0x3f4c422a, v37
	v_mul_f32_e32 v37, 0x3d372713, v27
	v_mul_f32_e32 v37, v37, v27
	v_mov_b32_e32 v38, v27
	v_mul_f32_e32 v25, 0x4038aa3b, v25
	v_fmac_f32_e32 v38, v37, v38
	v_exp_f32_e32 v25, v25
	v_mul_f32_e32 v36, 0x3f4c422a, v36
	v_mul_f32_e32 v37, 0x3f4c422a, v38
	v_mul_f32_e32 v36, 0x4038aa3b, v36
	v_mul_f32_e32 v37, 0x4038aa3b, v37
	v_exp_f32_e32 v36, v36
	v_exp_f32_e32 v37, v37
	v_add_f32_e32 v25, 1.0, v25
	v_rcp_f32_e32 v24, v24
	v_rcp_f32_e32 v25, v25
	v_add_f32_e32 v36, 1.0, v36
	v_add_f32_e32 v37, 1.0, v37
	v_rcp_f32_e32 v36, v36
	v_rcp_f32_e32 v37, v37
	v_pk_fma_f32 v[24:25], v[24:25], 2.0, 1.0 op_sel_hi:[1,0,0] neg_lo:[1,0,0] neg_hi:[1,0,0]
	v_pk_mul_f32 v[28:29], v[28:29], 0.5 op_sel_hi:[1,0]
	v_pk_add_f32 v[24:25], v[24:25], 1.0 op_sel_hi:[1,0]
	v_pk_mul_f32 v[26:27], v[26:27], 0.5 op_sel_hi:[1,0]
	v_pk_mul_f32 v[24:25], v[28:29], v[24:25]
	v_pk_fma_f32 v[28:29], v[36:37], 2.0, 1.0 op_sel_hi:[1,0,0] neg_lo:[1,0,0] neg_hi:[1,0,0]
	v_mul_f32_e32 v36, 0x3d372713, v30
	v_mul_f32_e32 v36, v36, v30
	v_mov_b32_e32 v37, v30
	v_fmac_f32_e32 v37, v36, v37
	v_mul_f32_e32 v36, 0x3f4c422a, v37
	v_mul_f32_e32 v36, 0x4038aa3b, v36
	v_exp_f32_e32 v36, v36
	v_pk_add_f32 v[28:29], v[28:29], 1.0 op_sel_hi:[1,0]
	v_mov_b32_e32 v37, v31
	v_pk_mul_f32 v[26:27], v[26:27], v[28:29]
	v_mul_f32_e32 v29, 0x3d372713, v32
	v_add_f32_e32 v28, 1.0, v36
	v_mul_f32_e32 v29, v29, v32
	v_mov_b32_e32 v36, v32
	v_fmac_f32_e32 v36, v29, v36
	v_mul_f32_e32 v29, 0x3d372713, v31
	v_mul_f32_e32 v29, v29, v31
	v_fmac_f32_e32 v37, v29, v37
	v_mul_f32_e32 v29, 0x3f4c422a, v37
	v_mul_f32_e32 v37, 0x3d372713, v33
	v_mul_f32_e32 v37, v37, v33
	v_mov_b32_e32 v38, v33
	v_mul_f32_e32 v29, 0x4038aa3b, v29
	v_fmac_f32_e32 v38, v37, v38
	v_exp_f32_e32 v29, v29
	v_mul_f32_e32 v36, 0x3f4c422a, v36
	v_mul_f32_e32 v37, 0x3f4c422a, v38
	v_mul_f32_e32 v36, 0x4038aa3b, v36
	v_mul_f32_e32 v37, 0x4038aa3b, v37
	v_exp_f32_e32 v36, v36
	v_exp_f32_e32 v37, v37
	v_add_f32_e32 v29, 1.0, v29
	v_rcp_f32_e32 v28, v28
	v_rcp_f32_e32 v29, v29
	v_add_f32_e32 v36, 1.0, v36
	v_add_f32_e32 v37, 1.0, v37
	v_rcp_f32_e32 v36, v36
	v_rcp_f32_e32 v37, v37
	v_pk_fma_f32 v[28:29], v[28:29], 2.0, 1.0 op_sel_hi:[1,0,0] neg_lo:[1,0,0] neg_hi:[1,0,0]
	v_pk_mul_f32 v[30:31], v[30:31], 0.5 op_sel_hi:[1,0]
	v_pk_add_f32 v[28:29], v[28:29], 1.0 op_sel_hi:[1,0]
	v_pk_mul_f32 v[32:33], v[32:33], 0.5 op_sel_hi:[1,0]
	v_pk_mul_f32 v[28:29], v[30:31], v[28:29]
	v_pk_fma_f32 v[30:31], v[36:37], 2.0, 1.0 op_sel_hi:[1,0,0] neg_lo:[1,0,0] neg_hi:[1,0,0]
	v_mov_b32_e32 v36, v25
	v_pk_add_f32 v[30:31], v[30:31], 1.0 op_sel_hi:[1,0]
	v_mov_b32_e32 v37, v29
	v_pk_mul_f32 v[30:31], v[32:33], v[30:31]
	v_mov_b32_e32 v32, v24
	v_mov_b32_e32 v33, v28
	v_pk_add_f32 v[32:33], v[32:33], v[36:37]
	v_mov_b32_e32 v36, v30
	v_mov_b32_e32 v37, v26
	v_mov_b32_e32 v38, v31
	s_waitcnt lgkmcnt(0)
	v_mov_b32_e32 v39, v27
	v_pk_add_f32 v[36:37], v[36:37], v[38:39]
	v_add_f32_e32 v32, v32, v33
	v_add_f32_e32 v32, v37, v32
	v_add_f32_e32 v32, v36, v32
	s_waitcnt lgkmcnt(0)
	s_nop 1
	v_add_f32_dpp v32, v32, v32 quad_perm:[1,0,3,2] row_mask:0xf bank_mask:0xf
	s_nop 1
	v_add_f32_dpp v32, v32, v32 quad_perm:[2,3,0,1] row_mask:0xf bank_mask:0xf
	s_nop 1
	v_add_f32_dpp v32, v32, v32 row_half_mirror row_mask:0xf bank_mask:0xf
	s_nop 1
	v_add_f32_dpp v32, v32, v32 row_mirror row_mask:0xf bank_mask:0xf
	v_mov_b32_e32 v33, v32
	s_nop 1
	v_permlane16_swap_b32 v33, v32
	v_add_f32_e32 v32, v32, v33
	v_mov_b32_e32 v33, v32
	s_nop 1
	v_permlane32_swap_b32 v33, v32
	v_add_f32_e32 v32, v32, v33
	v_fmamk_f32 v29, v32, 0xbb000000, v29
	v_fmamk_f32 v25, v32, 0xbb000000, v25
	v_fmac_f32_e32 v28, 0xbb000000, v32
	v_fmac_f32_e32 v24, 0xbb000000, v32
	v_fmamk_f32 v31, v32, 0xbb000000, v31
	v_fmac_f32_e32 v30, 0xbb000000, v32
	v_fmamk_f32 v27, v32, 0xbb000000, v27
	v_fmac_f32_e32 v26, 0xbb000000, v32
	v_mul_f32_e32 v32, v25, v25
	v_mul_f32_e32 v33, v29, v29
	v_fmac_f32_e32 v32, v24, v24
	v_fmac_f32_e32 v33, v28, v28
	v_add_f32_e32 v32, v32, v33
	v_mul_f32_e32 v33, v27, v27
	v_fmac_f32_e32 v33, v26, v26
	v_add_f32_e32 v32, v33, v32
	v_mul_f32_e32 v33, v31, v31
	v_fmac_f32_e32 v33, v30, v30
	v_add_f32_e32 v32, v33, v32
	s_waitcnt lgkmcnt(0)
	s_nop 1
	v_add_f32_dpp v32, v32, v32 quad_perm:[1,0,3,2] row_mask:0xf bank_mask:0xf
	s_nop 1
	v_add_f32_dpp v32, v32, v32 quad_perm:[2,3,0,1] row_mask:0xf bank_mask:0xf
	s_nop 1
	v_add_f32_dpp v32, v32, v32 row_half_mirror row_mask:0xf bank_mask:0xf
	s_nop 1
	v_add_f32_dpp v32, v32, v32 row_mirror row_mask:0xf bank_mask:0xf
	v_mov_b32_e32 v33, v32
	s_nop 1
	v_permlane16_swap_b32 v33, v32
	v_add_f32_e32 v32, v32, v33
	ds_bpermute_b32 v33, v59, v32
	s_and_saveexec_b64 s[2:3], s[38:39]
	s_cbranch_execz .LBB0_553
; __device__ __forceinline__ unsigned f2bf(float f) { unsigned u = __builtin_bit_cast(unsigned, f); return (u + 0x7fffu + ((u >> 16) & 1u)) >> 16; }
; __device__ __forceinline__ void gmlp_item(Frame& F, const Args& a, int l, int chunk, int g, const bf16* P, bf16* ACTA) {
;     ...
;         for (int i = 0; i < 8; ++i) {
;             const int s = w * 16 + i0 + i; f32x4 x0 = xa[i], x1 = xb[i];
; #pragma unroll
;             for (int j = 0; j < 4; ++j) { x0[j] = gelu_tanh(x0[j]); x1[j] = gelu_tanh(x1[j]); }
;             const float mean = wave_sum((x0[0] + x0[1]) + (x0[2] + x0[3]) + (x1[0] + x1[1]) + (x1[2] + x1[3])) * (1.f / 512.f);
;     ...
;             const float rstd = 1.0f / sqrtf(var + 1e-5f);
;             const f32x4 xm = myj ? x1 : x0;
;             if ((lane >> 5) == (g & 1)) {
;                 const int cl = 4 * (lane - mylo);
; #pragma unroll
;                 for (int j = 0; j < 4; ++j) Vt[(cl + j) * 136 + s] = (bf16)f2bf(xm[j] * rstd * lgv[j] + lbv[j]);
	v_cndmask_b32_e64 v24, v26, v24, s[0:1]
	s_waitcnt lgkmcnt(0)
	v_add_f32_e32 v26, v32, v33
	v_fmamk_f32 v26, v26, 0x3b000000, v215
	v_cndmask_b32_e64 v25, v27, v25, s[0:1]
	v_cmp_gt_f32_e32 vcc, s67, v26
	v_mul_f32_e32 v27, 0x4f800000, v26
	v_cndmask_b32_e64 v28, v30, v28, s[0:1]
	v_cndmask_b32_e32 v26, v26, v27, vcc
	v_sqrt_f32_e32 v27, v26
	v_cndmask_b32_e64 v29, v31, v29, s[0:1]
	v_add_u32_e32 v30, -1, v27
	v_fma_f32 v31, -v30, v27, v26
	v_cmp_ge_f32_e64 s[4:5], 0, v31
	v_add_u32_e32 v31, 1, v27
	s_nop 0
	v_cndmask_b32_e64 v30, v27, v30, s[4:5]
	v_fma_f32 v27, -v31, v27, v26
	v_cmp_lt_f32_e64 s[4:5], 0, v27
	s_nop 1
	v_cndmask_b32_e64 v27, v30, v31, s[4:5]
	v_mul_f32_e32 v30, 0x37800000, v27
	v_cndmask_b32_e32 v27, v27, v30, vcc
	v_cmp_class_f32_e32 vcc, v26, v213
	s_nop 1
	v_cndmask_b32_e32 v26, v27, v26, vcc
	v_div_scale_f32 v27, s[4:5], v26, v26, 1.0
	v_rcp_f32_e32 v30, v27
	s_nop 0
	v_fma_f32 v31, -v27, v30, 1.0
	v_fmac_f32_e32 v30, v31, v30
	v_div_scale_f32 v31, vcc, 1.0, v26, 1.0
	v_mul_f32_e32 v32, v31, v30
	v_fma_f32 v33, -v27, v32, v31
	v_fmac_f32_e32 v32, v33, v30
	v_fma_f32 v27, -v27, v32, v31
	v_div_fmas_f32 v27, v27, v30, v32
	v_div_fixup_f32 v26, v27, v26, 1.0
	v_mul_f32_e32 v24, v24, v26
	v_fma_f32 v24, v2, v24, v6
	v_bfe_u32 v27, v24, 16, 1
	v_add3_u32 v24, v24, v27, s7
	ds_write_b16_d16_hi v47, v24 offset:8
	v_mul_f32_e32 v24, v25, v26
	v_fma_f32 v24, v3, v24, v7
	v_bfe_u32 v25, v24, 16, 1
	v_add3_u32 v24, v24, v25, s7
	ds_write_b16_d16_hi v47, v24 offset:280
	v_mul_f32_e32 v24, v28, v26
	v_fma_f32 v24, v4, v24, v8
	v_bfe_u32 v25, v24, 16, 1
	v_add3_u32 v24, v24, v25, s7
	ds_write_b16_d16_hi v47, v24 offset:552
	v_mul_f32_e32 v24, v29, v26
	v_fma_f32 v24, v5, v24, v9
	v_bfe_u32 v25, v24, 16, 1
	v_add3_u32 v24, v24, v25, s7
	ds_write_b16_d16_hi v47, v24 offset:824
.LBB0_553:
	s_or_b64 exec, exec, s[2:3]
	v_lshlrev_b32_e32 v24, 16, v22
	v_lshlrev_b32_e32 v26, 16, v23
	v_and_b32_e32 v27, 0xffff0000, v23
	v_mul_f32_e32 v23, 0x3d372713, v24
	v_mul_f32_e32 v23, v23, v24
	v_mov_b32_e32 v28, v24
	v_fmac_f32_e32 v28, v23, v28
	v_mul_f32_e32 v23, 0x3f4c422a, v28
	v_mul_f32_e32 v23, 0x4038aa3b, v23
	v_exp_f32_e32 v30, v23
	v_and_b32_e32 v25, 0xffff0000, v22
	v_lshlrev_b32_e32 v22, 16, v20
	v_lshlrev_b32_e32 v28, 16, v21
	v_and_b32_e32 v29, 0xffff0000, v21
	v_mul_f32_e32 v21, 0x3d372713, v22
	v_and_b32_e32 v23, 0xffff0000, v20
	v_add_f32_e32 v20, 1.0, v30
	v_mul_f32_e32 v21, v21, v22
	v_mov_b32_e32 v30, v22
	v_fmac_f32_e32 v30, v21, v30
	v_mul_f32_e32 v21, 0x3d372713, v25
	v_mul_f32_e32 v21, v21, v25
	v_mov_b32_e32 v31, v25
	v_fmac_f32_e32 v31, v21, v31
	v_mul_f32_e32 v21, 0x3f4c422a, v31
	v_mul_f32_e32 v31, 0x3d372713, v23
	v_mul_f32_e32 v31, v31, v23
	v_mov_b32_e32 v32, v23
	v_mul_f32_e32 v21, 0x4038aa3b, v21
	v_fmac_f32_e32 v32, v31, v32
	v_exp_f32_e32 v21, v21
	v_mul_f32_e32 v30, 0x3f4c422a, v30
	v_mul_f32_e32 v31, 0x3f4c422a, v32
	v_mul_f32_e32 v30, 0x4038aa3b, v30
	v_mul_f32_e32 v31, 0x4038aa3b, v31
	v_exp_f32_e32 v30, v30
	v_exp_f32_e32 v31, v31
	v_add_f32_e32 v21, 1.0, v21
	v_rcp_f32_e32 v20, v20
	v_rcp_f32_e32 v21, v21
	v_add_f32_e32 v30, 1.0, v30
	v_add_f32_e32 v31, 1.0, v31
	v_rcp_f32_e32 v30, v30
	v_rcp_f32_e32 v31, v31
	v_pk_fma_f32 v[20:21], v[20:21], 2.0, 1.0 op_sel_hi:[1,0,0] neg_lo:[1,0,0] neg_hi:[1,0,0]
	v_pk_mul_f32 v[24:25], v[24:25], 0.5 op_sel_hi:[1,0]
	v_pk_add_f32 v[20:21], v[20:21], 1.0 op_sel_hi:[1,0]
	v_pk_mul_f32 v[22:23], v[22:23], 0.5 op_sel_hi:[1,0]
	v_pk_mul_f32 v[20:21], v[24:25], v[20:21]
	v_pk_fma_f32 v[24:25], v[30:31], 2.0, 1.0 op_sel_hi:[1,0,0] neg_lo:[1,0,0] neg_hi:[1,0,0]
	v_mul_f32_e32 v30, 0x3d372713, v26
	v_mul_f32_e32 v30, v30, v26
	v_mov_b32_e32 v31, v26
	v_fmac_f32_e32 v31, v30, v31
	v_mul_f32_e32 v30, 0x3f4c422a, v31
	v_mul_f32_e32 v30, 0x4038aa3b, v30
	v_exp_f32_e32 v30, v30
	v_pk_add_f32 v[24:25], v[24:25], 1.0 op_sel_hi:[1,0]
	v_mov_b32_e32 v31, v27
	v_pk_mul_f32 v[22:23], v[22:23], v[24:25]
	v_mul_f32_e32 v25, 0x3d372713, v28
	v_add_f32_e32 v24, 1.0, v30
	v_mul_f32_e32 v25, v25, v28
	v_mov_b32_e32 v30, v28
	v_fmac_f32_e32 v30, v25, v30
	v_mul_f32_e32 v25, 0x3d372713, v27
	v_mul_f32_e32 v25, v25, v27
	v_fmac_f32_e32 v31, v25, v31
	v_mul_f32_e32 v25, 0x3f4c422a, v31
	v_mul_f32_e32 v31, 0x3d372713, v29
	v_mul_f32_e32 v31, v31, v29
	v_mov_b32_e32 v32, v29
	v_mul_f32_e32 v25, 0x4038aa3b, v25
	v_fmac_f32_e32 v32, v31, v32
	v_exp_f32_e32 v25, v25
	v_mul_f32_e32 v30, 0x3f4c422a, v30
	v_mul_f32_e32 v31, 0x3f4c422a, v32
	v_mul_f32_e32 v30, 0x4038aa3b, v30
	v_mul_f32_e32 v31, 0x4038aa3b, v31
	v_exp_f32_e32 v30, v30
	v_exp_f32_e32 v31, v31
	v_add_f32_e32 v25, 1.0, v25
	v_rcp_f32_e32 v24, v24
	v_rcp_f32_e32 v25, v25
	v_add_f32_e32 v30, 1.0, v30
	v_add_f32_e32 v31, 1.0, v31
	v_rcp_f32_e32 v30, v30
	v_rcp_f32_e32 v31, v31
	v_pk_fma_f32 v[24:25], v[24:25], 2.0, 1.0 op_sel_hi:[1,0,0] neg_lo:[1,0,0] neg_hi:[1,0,0]
	v_pk_mul_f32 v[26:27], v[26:27], 0.5 op_sel_hi:[1,0]
	v_pk_add_f32 v[24:25], v[24:25], 1.0 op_sel_hi:[1,0]
	v_pk_mul_f32 v[28:29], v[28:29], 0.5 op_sel_hi:[1,0]
	v_pk_mul_f32 v[24:25], v[26:27], v[24:25]
	v_pk_fma_f32 v[26:27], v[30:31], 2.0, 1.0 op_sel_hi:[1,0,0] neg_lo:[1,0,0] neg_hi:[1,0,0]
	v_mov_b32_e32 v30, v21
	v_pk_add_f32 v[26:27], v[26:27], 1.0 op_sel_hi:[1,0]
	v_mov_b32_e32 v31, v25
	v_pk_mul_f32 v[26:27], v[28:29], v[26:27]
	v_mov_b32_e32 v28, v20
	v_mov_b32_e32 v29, v24
	v_pk_add_f32 v[28:29], v[28:29], v[30:31]
	v_mov_b32_e32 v30, v26
	v_mov_b32_e32 v31, v22
	v_mov_b32_e32 v32, v27
	s_waitcnt lgkmcnt(0)
	v_mov_b32_e32 v33, v23
	v_pk_add_f32 v[30:31], v[30:31], v[32:33]
	v_add_f32_e32 v28, v28, v29
	v_add_f32_e32 v28, v31, v28
	v_add_f32_e32 v28, v30, v28
	s_waitcnt lgkmcnt(0)
; __device__ __forceinline__ unsigned f2bf(float f) { unsigned u = __builtin_bit_cast(unsigned, f); return (u + 0x7fffu + ((u >> 16) & 1u)) >> 16; }
; __device__ __forceinline__ void gmlp_item(Frame& F, const Args& a, int l, int chunk, int g, const bf16* P, bf16* ACTA) {
;     ...
;         for (int i = 0; i < 8; ++i) {
;             const int s = w * 16 + i0 + i; f32x4 x0 = xa[i], x1 = xb[i];
; #pragma unroll
;             for (int j = 0; j < 4; ++j) { x0[j] = gelu_tanh(x0[j]); x1[j] = gelu_tanh(x1[j]); }
;             const float mean = wave_sum((x0[0] + x0[1]) + (x0[2] + x0[3]) + (x1[0] + x1[1]) + (x1[2] + x1[3])) * (1.f / 512.f);
;             x0 -= mean; x1 -= mean;
;             const float var = wave_sum((x0[0] * x0[0] + x0[1] * x0[1]) + (x0[2] * x0[2] + x0[3] * x0[3]) + (x1[0] * x1[0] + x1[1] * x1[1]) + (x1[2] * x1[2] + x1[3] * x1[3])) * (1.f / 512.f);
;             const float rstd = 1.0f / sqrtf(var + 1e-5f);
;             const f32x4 xm = myj ? x1 : x0;
;             if ((lane >> 5) == (g & 1)) {
;                 const int cl = 4 * (lane - mylo);
; #pragma unroll
;                 for (int j = 0; j < 4; ++j) Vt[(cl + j) * 136 + s] = (bf16)f2bf(xm[j] * rstd * lgv[j] + lbv[j]);
	s_nop 1
	v_add_f32_dpp v28, v28, v28 quad_perm:[1,0,3,2] row_mask:0xf bank_mask:0xf
	s_nop 1
	v_add_f32_dpp v28, v28, v28 quad_perm:[2,3,0,1] row_mask:0xf bank_mask:0xf
	s_nop 1
	v_add_f32_dpp v28, v28, v28 row_half_mirror row_mask:0xf bank_mask:0xf
	s_nop 1
	v_add_f32_dpp v28, v28, v28 row_mirror row_mask:0xf bank_mask:0xf
	v_mov_b32_e32 v29, v28
	s_nop 1
	v_permlane16_swap_b32 v29, v28
	v_add_f32_e32 v28, v28, v29
	v_mov_b32_e32 v29, v28
	s_nop 1
	v_permlane32_swap_b32 v29, v28
	v_add_f32_e32 v28, v28, v29
	v_fmamk_f32 v25, v28, 0xbb000000, v25
	v_fmamk_f32 v21, v28, 0xbb000000, v21
	v_fmac_f32_e32 v24, 0xbb000000, v28
	v_fmac_f32_e32 v20, 0xbb000000, v28
	v_fmamk_f32 v27, v28, 0xbb000000, v27
	v_fmac_f32_e32 v26, 0xbb000000, v28
	v_fmamk_f32 v23, v28, 0xbb000000, v23
	v_fmac_f32_e32 v22, 0xbb000000, v28
	v_mul_f32_e32 v28, v21, v21
	v_mul_f32_e32 v29, v25, v25
	v_fmac_f32_e32 v28, v20, v20
	v_fmac_f32_e32 v29, v24, v24
	v_add_f32_e32 v28, v28, v29
	v_mul_f32_e32 v29, v23, v23
	v_fmac_f32_e32 v29, v22, v22
	v_add_f32_e32 v28, v29, v28
	v_mul_f32_e32 v29, v27, v27
	v_fmac_f32_e32 v29, v26, v26
	v_add_f32_e32 v28, v29, v28
	s_waitcnt lgkmcnt(0)
	s_nop 1
	v_add_f32_dpp v28, v28, v28 quad_perm:[1,0,3,2] row_mask:0xf bank_mask:0xf
	s_nop 1
	v_add_f32_dpp v28, v28, v28 quad_perm:[2,3,0,1] row_mask:0xf bank_mask:0xf
	s_nop 1
	v_add_f32_dpp v28, v28, v28 row_half_mirror row_mask:0xf bank_mask:0xf
	s_nop 1
	v_add_f32_dpp v28, v28, v28 row_mirror row_mask:0xf bank_mask:0xf
	v_mov_b32_e32 v29, v28
	s_nop 1
	v_permlane16_swap_b32 v29, v28
	v_add_f32_e32 v28, v28, v29
	ds_bpermute_b32 v29, v59, v28
	s_and_saveexec_b64 s[2:3], s[38:39]
	s_cbranch_execz .LBB0_555
	v_cndmask_b32_e64 v20, v22, v20, s[0:1]
	s_waitcnt lgkmcnt(0)
	v_add_f32_e32 v22, v28, v29
	v_fmamk_f32 v22, v22, 0x3b000000, v215
	v_cndmask_b32_e64 v21, v23, v21, s[0:1]
	v_cmp_gt_f32_e32 vcc, s67, v22
	v_mul_f32_e32 v23, 0x4f800000, v22
	v_cndmask_b32_e64 v24, v26, v24, s[0:1]
	v_cndmask_b32_e32 v22, v22, v23, vcc
	v_sqrt_f32_e32 v23, v22
	v_cndmask_b32_e64 v25, v27, v25, s[0:1]
	v_add_u32_e32 v26, -1, v23
	v_fma_f32 v27, -v26, v23, v22
	v_cmp_ge_f32_e64 s[4:5], 0, v27
	v_add_u32_e32 v27, 1, v23
	s_nop 0
	v_cndmask_b32_e64 v26, v23, v26, s[4:5]
	v_fma_f32 v23, -v27, v23, v22
	v_cmp_lt_f32_e64 s[4:5], 0, v23
	s_nop 1
	v_cndmask_b32_e64 v23, v26, v27, s[4:5]
	v_mul_f32_e32 v26, 0x37800000, v23
	v_cndmask_b32_e32 v23, v23, v26, vcc
	v_cmp_class_f32_e32 vcc, v22, v213
	s_nop 1
	v_cndmask_b32_e32 v22, v23, v22, vcc
	v_div_scale_f32 v23, s[4:5], v22, v22, 1.0
	v_rcp_f32_e32 v26, v23
	s_nop 0
	v_fma_f32 v27, -v23, v26, 1.0
	v_fmac_f32_e32 v26, v27, v26
	v_div_scale_f32 v27, vcc, 1.0, v22, 1.0
	v_mul_f32_e32 v28, v27, v26
	v_fma_f32 v29, -v23, v28, v27
	v_fmac_f32_e32 v28, v29, v26
	v_fma_f32 v23, -v23, v28, v27
	v_div_fmas_f32 v23, v23, v26, v28
	v_div_fixup_f32 v22, v23, v22, 1.0
	v_mul_f32_e32 v20, v20, v22
	v_fma_f32 v20, v2, v20, v6
	v_bfe_u32 v23, v20, 16, 1
	v_add3_u32 v20, v20, v23, s7
	ds_write_b16_d16_hi v47, v20 offset:10
	v_mul_f32_e32 v20, v21, v22
	v_fma_f32 v20, v3, v20, v7
	v_bfe_u32 v21, v20, 16, 1
	v_add3_u32 v20, v20, v21, s7
	ds_write_b16_d16_hi v47, v20 offset:282
	v_mul_f32_e32 v20, v24, v22
	v_fma_f32 v20, v4, v20, v8
	v_bfe_u32 v21, v20, 16, 1
	v_add3_u32 v20, v20, v21, s7
	ds_write_b16_d16_hi v47, v20 offset:554
	v_mul_f32_e32 v20, v25, v22
	v_fma_f32 v20, v5, v20, v9
	v_bfe_u32 v21, v20, 16, 1
	v_add3_u32 v20, v20, v21, s7
	ds_write_b16_d16_hi v47, v20 offset:826
.LBB0_555:
	s_or_b64 exec, exec, s[2:3]
	s_waitcnt vmcnt(3)
	v_lshlrev_b32_e32 v20, 16, v18
	v_lshlrev_b32_e32 v22, 16, v19
	v_and_b32_e32 v23, 0xffff0000, v19
	v_mul_f32_e32 v19, 0x3d372713, v20
	v_mul_f32_e32 v19, v19, v20
	v_mov_b32_e32 v24, v20
	v_fmac_f32_e32 v24, v19, v24
	v_mul_f32_e32 v19, 0x3f4c422a, v24
	v_mul_f32_e32 v19, 0x4038aa3b, v19
	v_exp_f32_e32 v26, v19
	v_and_b32_e32 v21, 0xffff0000, v18
	s_waitcnt vmcnt(2)
	v_lshlrev_b32_e32 v18, 16, v16
	v_lshlrev_b32_e32 v24, 16, v17
	v_and_b32_e32 v25, 0xffff0000, v17
	v_mul_f32_e32 v17, 0x3d372713, v18
	v_and_b32_e32 v19, 0xffff0000, v16
	v_add_f32_e32 v16, 1.0, v26
	v_mul_f32_e32 v17, v17, v18
	v_mov_b32_e32 v26, v18
	v_fmac_f32_e32 v26, v17, v26
	v_mul_f32_e32 v17, 0x3d372713, v21
	v_mul_f32_e32 v17, v17, v21
	v_mov_b32_e32 v27, v21
	v_fmac_f32_e32 v27, v17, v27
	v_mul_f32_e32 v17, 0x3f4c422a, v27
	v_mul_f32_e32 v27, 0x3d372713, v19
	v_mul_f32_e32 v27, v27, v19
	v_mov_b32_e32 v28, v19
	v_mul_f32_e32 v17, 0x4038aa3b, v17
	v_fmac_f32_e32 v28, v27, v28
	v_exp_f32_e32 v17, v17
	v_mul_f32_e32 v26, 0x3f4c422a, v26
	v_mul_f32_e32 v27, 0x3f4c422a, v28
	v_mul_f32_e32 v26, 0x4038aa3b, v26
	v_mul_f32_e32 v27, 0x4038aa3b, v27
	v_exp_f32_e32 v26, v26
	v_exp_f32_e32 v27, v27
	v_add_f32_e32 v17, 1.0, v17
	v_rcp_f32_e32 v16, v16
	v_rcp_f32_e32 v17, v17
	v_add_f32_e32 v26, 1.0, v26
	v_add_f32_e32 v27, 1.0, v27
	v_rcp_f32_e32 v26, v26
	v_rcp_f32_e32 v27, v27
	v_pk_fma_f32 v[16:17], v[16:17], 2.0, 1.0 op_sel_hi:[1,0,0] neg_lo:[1,0,0] neg_hi:[1,0,0]
	v_pk_mul_f32 v[20:21], v[20:21], 0.5 op_sel_hi:[1,0]
	v_pk_add_f32 v[16:17], v[16:17], 1.0 op_sel_hi:[1,0]
	v_pk_mul_f32 v[18:19], v[18:19], 0.5 op_sel_hi:[1,0]
	v_pk_mul_f32 v[16:17], v[20:21], v[16:17]
	v_pk_fma_f32 v[20:21], v[26:27], 2.0, 1.0 op_sel_hi:[1,0,0] neg_lo:[1,0,0] neg_hi:[1,0,0]
	v_mul_f32_e32 v26, 0x3d372713, v22
	v_mul_f32_e32 v26, v26, v22
	v_mov_b32_e32 v27, v22
	v_fmac_f32_e32 v27, v26, v27
	v_mul_f32_e32 v26, 0x3f4c422a, v27
	v_mul_f32_e32 v26, 0x4038aa3b, v26
	v_exp_f32_e32 v26, v26
	v_pk_add_f32 v[20:21], v[20:21], 1.0 op_sel_hi:[1,0]
	v_mov_b32_e32 v27, v23
	v_pk_mul_f32 v[18:19], v[18:19], v[20:21]
; __device__ __forceinline__ unsigned f2bf(float f) { unsigned u = __builtin_bit_cast(unsigned, f); return (u + 0x7fffu + ((u >> 16) & 1u)) >> 16; }
; __device__ __forceinline__ void gmlp_item(Frame& F, const Args& a, int l, int chunk, int g, const bf16* P, bf16* ACTA) {
;     ...
;         for (int i = 0; i < 8; ++i) {
;             const int s = w * 16 + i0 + i; f32x4 x0 = xa[i], x1 = xb[i];
; #pragma unroll
;             for (int j = 0; j < 4; ++j) { x0[j] = gelu_tanh(x0[j]); x1[j] = gelu_tanh(x1[j]); }
;             const float mean = wave_sum((x0[0] + x0[1]) + (x0[2] + x0[3]) + (x1[0] + x1[1]) + (x1[2] + x1[3])) * (1.f / 512.f);
;             x0 -= mean; x1 -= mean;
;             const float var = wave_sum((x0[0] * x0[0] + x0[1] * x0[1]) + (x0[2] * x0[2] + x0[3] * x0[3]) + (x1[0] * x1[0] + x1[1] * x1[1]) + (x1[2] * x1[2] + x1[3] * x1[3])) * (1.f / 512.f);
;             const float rstd = 1.0f / sqrtf(var + 1e-5f);
;             const f32x4 xm = myj ? x1 : x0;
;             if ((lane >> 5) == (g & 1)) {
;                 const int cl = 4 * (lane - mylo);
; #pragma unroll
;                 for (int j = 0; j < 4; ++j) Vt[(cl + j) * 136 + s] = (bf16)f2bf(xm[j] * rstd * lgv[j] + lbv[j]);
	v_mul_f32_e32 v21, 0x3d372713, v24
	v_add_f32_e32 v20, 1.0, v26
	v_mul_f32_e32 v21, v21, v24
	v_mov_b32_e32 v26, v24
	v_fmac_f32_e32 v26, v21, v26
	v_mul_f32_e32 v21, 0x3d372713, v23
	v_mul_f32_e32 v21, v21, v23
	v_fmac_f32_e32 v27, v21, v27
	v_mul_f32_e32 v21, 0x3f4c422a, v27
	v_mul_f32_e32 v27, 0x3d372713, v25
	v_mul_f32_e32 v27, v27, v25
	v_mov_b32_e32 v28, v25
	v_mul_f32_e32 v21, 0x4038aa3b, v21
	v_fmac_f32_e32 v28, v27, v28
	v_exp_f32_e32 v21, v21
	v_mul_f32_e32 v26, 0x3f4c422a, v26
	v_mul_f32_e32 v27, 0x3f4c422a, v28
	v_mul_f32_e32 v26, 0x4038aa3b, v26
	v_mul_f32_e32 v27, 0x4038aa3b, v27
	v_exp_f32_e32 v26, v26
	v_exp_f32_e32 v27, v27
	v_add_f32_e32 v21, 1.0, v21
	v_rcp_f32_e32 v20, v20
	v_rcp_f32_e32 v21, v21
	v_add_f32_e32 v26, 1.0, v26
	v_add_f32_e32 v27, 1.0, v27
	v_rcp_f32_e32 v26, v26
	v_rcp_f32_e32 v27, v27
	v_pk_fma_f32 v[20:21], v[20:21], 2.0, 1.0 op_sel_hi:[1,0,0] neg_lo:[1,0,0] neg_hi:[1,0,0]
	v_pk_mul_f32 v[22:23], v[22:23], 0.5 op_sel_hi:[1,0]
	v_pk_add_f32 v[20:21], v[20:21], 1.0 op_sel_hi:[1,0]
	v_pk_mul_f32 v[24:25], v[24:25], 0.5 op_sel_hi:[1,0]
	v_pk_mul_f32 v[20:21], v[22:23], v[20:21]
	v_pk_fma_f32 v[22:23], v[26:27], 2.0, 1.0 op_sel_hi:[1,0,0] neg_lo:[1,0,0] neg_hi:[1,0,0]
	v_mov_b32_e32 v26, v17
	v_pk_add_f32 v[22:23], v[22:23], 1.0 op_sel_hi:[1,0]
	v_mov_b32_e32 v27, v21
	v_pk_mul_f32 v[22:23], v[24:25], v[22:23]
	v_mov_b32_e32 v24, v16
	v_mov_b32_e32 v25, v20
	v_pk_add_f32 v[24:25], v[24:25], v[26:27]
	v_mov_b32_e32 v26, v22
	v_mov_b32_e32 v27, v18
	v_mov_b32_e32 v28, v23
	s_waitcnt lgkmcnt(0)
	v_mov_b32_e32 v29, v19
	v_pk_add_f32 v[26:27], v[26:27], v[28:29]
	v_add_f32_e32 v24, v24, v25
	v_add_f32_e32 v24, v27, v24
	v_add_f32_e32 v24, v26, v24
	s_waitcnt lgkmcnt(0)
	s_nop 1
	v_add_f32_dpp v24, v24, v24 quad_perm:[1,0,3,2] row_mask:0xf bank_mask:0xf
	s_nop 1
	v_add_f32_dpp v24, v24, v24 quad_perm:[2,3,0,1] row_mask:0xf bank_mask:0xf
	s_nop 1
	v_add_f32_dpp v24, v24, v24 row_half_mirror row_mask:0xf bank_mask:0xf
	s_nop 1
	v_add_f32_dpp v24, v24, v24 row_mirror row_mask:0xf bank_mask:0xf
	v_mov_b32_e32 v25, v24
	s_nop 1
	v_permlane16_swap_b32 v25, v24
	v_add_f32_e32 v24, v24, v25
	v_mov_b32_e32 v25, v24
	s_nop 1
	v_permlane32_swap_b32 v25, v24
	v_add_f32_e32 v24, v24, v25
	v_fmamk_f32 v21, v24, 0xbb000000, v21
	v_fmamk_f32 v17, v24, 0xbb000000, v17
	v_fmac_f32_e32 v20, 0xbb000000, v24
	v_fmac_f32_e32 v16, 0xbb000000, v24
	v_fmamk_f32 v23, v24, 0xbb000000, v23
	v_fmac_f32_e32 v22, 0xbb000000, v24
	v_fmamk_f32 v19, v24, 0xbb000000, v19
	v_fmac_f32_e32 v18, 0xbb000000, v24
	v_mul_f32_e32 v24, v17, v17
	v_mul_f32_e32 v25, v21, v21
	v_fmac_f32_e32 v24, v16, v16
	v_fmac_f32_e32 v25, v20, v20
	v_add_f32_e32 v24, v24, v25
	v_mul_f32_e32 v25, v19, v19
	v_fmac_f32_e32 v25, v18, v18
	v_add_f32_e32 v24, v25, v24
	v_mul_f32_e32 v25, v23, v23
	v_fmac_f32_e32 v25, v22, v22
	v_add_f32_e32 v24, v25, v24
	s_waitcnt lgkmcnt(0)
	s_nop 1
	v_add_f32_dpp v24, v24, v24 quad_perm:[1,0,3,2] row_mask:0xf bank_mask:0xf
	s_nop 1
	v_add_f32_dpp v24, v24, v24 quad_perm:[2,3,0,1] row_mask:0xf bank_mask:0xf
	s_nop 1
	v_add_f32_dpp v24, v24, v24 row_half_mirror row_mask:0xf bank_mask:0xf
	s_nop 1
	v_add_f32_dpp v24, v24, v24 row_mirror row_mask:0xf bank_mask:0xf
	v_mov_b32_e32 v25, v24
	s_nop 1
	v_permlane16_swap_b32 v25, v24
	v_add_f32_e32 v24, v24, v25
	ds_bpermute_b32 v25, v59, v24
	s_and_saveexec_b64 s[2:3], s[38:39]
	s_cbranch_execz .LBB0_557
	v_cndmask_b32_e64 v16, v18, v16, s[0:1]
	s_waitcnt lgkmcnt(0)
	v_add_f32_e32 v18, v24, v25
	v_fmamk_f32 v18, v18, 0x3b000000, v215
	v_cndmask_b32_e64 v17, v19, v17, s[0:1]
	v_cmp_gt_f32_e32 vcc, s67, v18
	v_mul_f32_e32 v19, 0x4f800000, v18
	v_cndmask_b32_e64 v20, v22, v20, s[0:1]
	v_cndmask_b32_e32 v18, v18, v19, vcc
	v_sqrt_f32_e32 v19, v18
	v_cndmask_b32_e64 v21, v23, v21, s[0:1]
	v_add_u32_e32 v22, -1, v19
	v_fma_f32 v23, -v22, v19, v18
	v_cmp_ge_f32_e64 s[4:5], 0, v23
	v_add_u32_e32 v23, 1, v19
	s_nop 0
	v_cndmask_b32_e64 v22, v19, v22, s[4:5]
	v_fma_f32 v19, -v23, v19, v18
	v_cmp_lt_f32_e64 s[4:5], 0, v19
	s_nop 1
	v_cndmask_b32_e64 v19, v22, v23, s[4:5]
	v_mul_f32_e32 v22, 0x37800000, v19
	v_cndmask_b32_e32 v19, v19, v22, vcc
	v_cmp_class_f32_e32 vcc, v18, v213
	s_nop 1
	v_cndmask_b32_e32 v18, v19, v18, vcc
	v_div_scale_f32 v19, s[4:5], v18, v18, 1.0
	v_rcp_f32_e32 v22, v19
	s_nop 0
	v_fma_f32 v23, -v19, v22, 1.0
	v_fmac_f32_e32 v22, v23, v22
	v_div_scale_f32 v23, vcc, 1.0, v18, 1.0
	v_mul_f32_e32 v24, v23, v22
	v_fma_f32 v25, -v19, v24, v23
	v_fmac_f32_e32 v24, v25, v22
	v_fma_f32 v19, -v19, v24, v23
	v_div_fmas_f32 v19, v19, v22, v24
	v_div_fixup_f32 v18, v19, v18, 1.0
	v_mul_f32_e32 v16, v16, v18
	v_fma_f32 v16, v2, v16, v6
	v_bfe_u32 v19, v16, 16, 1
	v_add3_u32 v16, v16, v19, s7
	ds_write_b16_d16_hi v47, v16 offset:12
	v_mul_f32_e32 v16, v17, v18
	v_fma_f32 v16, v3, v16, v7
	v_bfe_u32 v17, v16, 16, 1
	v_add3_u32 v16, v16, v17, s7
	ds_write_b16_d16_hi v47, v16 offset:284
	v_mul_f32_e32 v16, v20, v18
	v_fma_f32 v16, v4, v16, v8
	v_bfe_u32 v17, v16, 16, 1
	v_add3_u32 v16, v16, v17, s7
	ds_write_b16_d16_hi v47, v16 offset:556
	v_mul_f32_e32 v16, v21, v18
	v_fma_f32 v16, v5, v16, v9
	v_bfe_u32 v17, v16, 16, 1
	v_add3_u32 v16, v16, v17, s7
	ds_write_b16_d16_hi v47, v16 offset:828
; __device__ __forceinline__ void gmlp_item(Frame& F, const Args& a, int l, int chunk, int g, const bf16* P, bf16* ACTA) {
;     ...
;         for (int i = 0; i < 8; ++i) {
;             const int s = w * 16 + i0 + i; f32x4 x0 = xa[i], x1 = xb[i];
; #pragma unroll
;             for (int j = 0; j < 4; ++j) { x0[j] = gelu_tanh(x0[j]); x1[j] = gelu_tanh(x1[j]); }
;             const float mean = wave_sum((x0[0] + x0[1]) + (x0[2] + x0[3]) + (x1[0] + x1[1]) + (x1[2] + x1[3])) * (1.f / 512.f);
;             x0 -= mean; x1 -= mean;
;             const float var = wave_sum((x0[0] * x0[0] + x0[1] * x0[1]) + (x0[2] * x0[2] + x0[3] * x0[3]) + (x1[0] * x1[0] + x1[1] * x1[1]) + (x1[2] * x1[2] + x1[3] * x1[3])) * (1.f / 512.f);
.LBB0_557:
	s_or_b64 exec, exec, s[2:3]
	s_waitcnt vmcnt(1)
	v_lshlrev_b32_e32 v16, 16, v14
	v_lshlrev_b32_e32 v18, 16, v15
	v_and_b32_e32 v19, 0xffff0000, v15
	v_mul_f32_e32 v15, 0x3d372713, v16
	v_mul_f32_e32 v15, v15, v16
	v_mov_b32_e32 v20, v16
	v_fmac_f32_e32 v20, v15, v20
	v_mul_f32_e32 v15, 0x3f4c422a, v20
	v_mul_f32_e32 v15, 0x4038aa3b, v15
	v_exp_f32_e32 v22, v15
	v_and_b32_e32 v17, 0xffff0000, v14
	s_waitcnt vmcnt(0)
	v_lshlrev_b32_e32 v14, 16, v12
	v_lshlrev_b32_e32 v20, 16, v13
	v_and_b32_e32 v21, 0xffff0000, v13
	v_mul_f32_e32 v13, 0x3d372713, v14
	v_and_b32_e32 v15, 0xffff0000, v12
	v_add_f32_e32 v12, 1.0, v22
	v_mul_f32_e32 v13, v13, v14
	v_mov_b32_e32 v22, v14
	v_fmac_f32_e32 v22, v13, v22
	v_mul_f32_e32 v13, 0x3d372713, v17
	v_mul_f32_e32 v13, v13, v17
	v_mov_b32_e32 v23, v17
	v_fmac_f32_e32 v23, v13, v23
	v_mul_f32_e32 v13, 0x3f4c422a, v23
	v_mul_f32_e32 v23, 0x3d372713, v15
	v_mul_f32_e32 v23, v23, v15
	v_mov_b32_e32 v24, v15
	v_mul_f32_e32 v13, 0x4038aa3b, v13
	v_fmac_f32_e32 v24, v23, v24
	v_exp_f32_e32 v13, v13
	v_mul_f32_e32 v22, 0x3f4c422a, v22
	v_mul_f32_e32 v23, 0x3f4c422a, v24
	v_mul_f32_e32 v22, 0x4038aa3b, v22
	v_mul_f32_e32 v23, 0x4038aa3b, v23
	v_exp_f32_e32 v22, v22
	v_exp_f32_e32 v23, v23
	v_add_f32_e32 v13, 1.0, v13
	v_rcp_f32_e32 v12, v12
	v_rcp_f32_e32 v13, v13
	v_add_f32_e32 v22, 1.0, v22
	v_add_f32_e32 v23, 1.0, v23
	v_rcp_f32_e32 v22, v22
	v_rcp_f32_e32 v23, v23
	v_pk_fma_f32 v[12:13], v[12:13], 2.0, 1.0 op_sel_hi:[1,0,0] neg_lo:[1,0,0] neg_hi:[1,0,0]
	v_pk_mul_f32 v[16:17], v[16:17], 0.5 op_sel_hi:[1,0]
	v_pk_add_f32 v[12:13], v[12:13], 1.0 op_sel_hi:[1,0]
	v_pk_mul_f32 v[14:15], v[14:15], 0.5 op_sel_hi:[1,0]
	v_pk_mul_f32 v[12:13], v[16:17], v[12:13]
	v_pk_fma_f32 v[16:17], v[22:23], 2.0, 1.0 op_sel_hi:[1,0,0] neg_lo:[1,0,0] neg_hi:[1,0,0]
	v_mul_f32_e32 v22, 0x3d372713, v18
	v_mul_f32_e32 v22, v22, v18
	v_mov_b32_e32 v23, v18
	v_fmac_f32_e32 v23, v22, v23
	v_mul_f32_e32 v22, 0x3f4c422a, v23
	v_mul_f32_e32 v22, 0x4038aa3b, v22
	v_exp_f32_e32 v22, v22
	v_pk_add_f32 v[16:17], v[16:17], 1.0 op_sel_hi:[1,0]
	v_mov_b32_e32 v23, v19
	v_pk_mul_f32 v[14:15], v[14:15], v[16:17]
	v_mul_f32_e32 v17, 0x3d372713, v20
	v_add_f32_e32 v16, 1.0, v22
	v_mul_f32_e32 v17, v17, v20
	v_mov_b32_e32 v22, v20
	v_fmac_f32_e32 v22, v17, v22
	v_mul_f32_e32 v17, 0x3d372713, v19
	v_mul_f32_e32 v17, v17, v19
	v_fmac_f32_e32 v23, v17, v23
	v_mul_f32_e32 v17, 0x3f4c422a, v23
	v_mul_f32_e32 v23, 0x3d372713, v21
	v_mul_f32_e32 v23, v23, v21
	v_mov_b32_e32 v24, v21
	v_mul_f32_e32 v17, 0x4038aa3b, v17
	v_fmac_f32_e32 v24, v23, v24
	v_exp_f32_e32 v17, v17
	v_mul_f32_e32 v22, 0x3f4c422a, v22
	v_mul_f32_e32 v23, 0x3f4c422a, v24
	v_mul_f32_e32 v22, 0x4038aa3b, v22
	v_mul_f32_e32 v23, 0x4038aa3b, v23
	v_exp_f32_e32 v22, v22
	v_exp_f32_e32 v23, v23
	v_add_f32_e32 v17, 1.0, v17
	v_rcp_f32_e32 v16, v16
	v_rcp_f32_e32 v17, v17
	v_add_f32_e32 v22, 1.0, v22
	v_add_f32_e32 v23, 1.0, v23
	v_rcp_f32_e32 v22, v22
	v_rcp_f32_e32 v23, v23
	v_pk_fma_f32 v[16:17], v[16:17], 2.0, 1.0 op_sel_hi:[1,0,0] neg_lo:[1,0,0] neg_hi:[1,0,0]
	v_pk_mul_f32 v[18:19], v[18:19], 0.5 op_sel_hi:[1,0]
	v_pk_add_f32 v[16:17], v[16:17], 1.0 op_sel_hi:[1,0]
	v_pk_mul_f32 v[20:21], v[20:21], 0.5 op_sel_hi:[1,0]
	v_pk_mul_f32 v[16:17], v[18:19], v[16:17]
	v_pk_fma_f32 v[18:19], v[22:23], 2.0, 1.0 op_sel_hi:[1,0,0] neg_lo:[1,0,0] neg_hi:[1,0,0]
	v_mov_b32_e32 v22, v13
	v_pk_add_f32 v[18:19], v[18:19], 1.0 op_sel_hi:[1,0]
	v_mov_b32_e32 v23, v17
	v_pk_mul_f32 v[18:19], v[20:21], v[18:19]
	v_mov_b32_e32 v20, v12
	v_mov_b32_e32 v21, v16
	v_pk_add_f32 v[20:21], v[20:21], v[22:23]
	v_mov_b32_e32 v22, v18
	v_mov_b32_e32 v23, v14
	v_mov_b32_e32 v24, v19
	s_waitcnt lgkmcnt(0)
	v_mov_b32_e32 v25, v15
	v_pk_add_f32 v[22:23], v[22:23], v[24:25]
	v_add_f32_e32 v20, v20, v21
	v_add_f32_e32 v20, v23, v20
	v_add_f32_e32 v20, v22, v20
	s_waitcnt lgkmcnt(0)
	s_nop 1
	v_add_f32_dpp v20, v20, v20 quad_perm:[1,0,3,2] row_mask:0xf bank_mask:0xf
	s_nop 1
	v_add_f32_dpp v20, v20, v20 quad_perm:[2,3,0,1] row_mask:0xf bank_mask:0xf
	s_nop 1
	v_add_f32_dpp v20, v20, v20 row_half_mirror row_mask:0xf bank_mask:0xf
	s_nop 1
	v_add_f32_dpp v20, v20, v20 row_mirror row_mask:0xf bank_mask:0xf
	v_mov_b32_e32 v21, v20
	s_nop 1
	v_permlane16_swap_b32 v21, v20
	v_add_f32_e32 v20, v20, v21
	v_mov_b32_e32 v21, v20
	s_nop 1
	v_permlane32_swap_b32 v21, v20
	v_add_f32_e32 v20, v20, v21
	v_fmamk_f32 v17, v20, 0xbb000000, v17
	v_fmamk_f32 v13, v20, 0xbb000000, v13
	v_fmac_f32_e32 v16, 0xbb000000, v20
	v_fmac_f32_e32 v12, 0xbb000000, v20
	v_fmamk_f32 v19, v20, 0xbb000000, v19
	v_fmac_f32_e32 v18, 0xbb000000, v20
	v_fmamk_f32 v15, v20, 0xbb000000, v15
	v_fmac_f32_e32 v14, 0xbb000000, v20
	v_mul_f32_e32 v20, v13, v13
	v_mul_f32_e32 v21, v17, v17
	v_fmac_f32_e32 v20, v12, v12
	v_fmac_f32_e32 v21, v16, v16
	v_add_f32_e32 v20, v20, v21
	v_mul_f32_e32 v21, v15, v15
	v_fmac_f32_e32 v21, v14, v14
	v_add_f32_e32 v20, v21, v20
	v_mul_f32_e32 v21, v19, v19
	v_fmac_f32_e32 v21, v18, v18
	v_add_f32_e32 v20, v21, v20
	s_waitcnt lgkmcnt(0)
	s_nop 1
	v_add_f32_dpp v20, v20, v20 quad_perm:[1,0,3,2] row_mask:0xf bank_mask:0xf
	s_nop 1
	v_add_f32_dpp v20, v20, v20 quad_perm:[2,3,0,1] row_mask:0xf bank_mask:0xf
	s_nop 1
	v_add_f32_dpp v20, v20, v20 row_half_mirror row_mask:0xf bank_mask:0xf
	s_nop 1
	v_add_f32_dpp v20, v20, v20 row_mirror row_mask:0xf bank_mask:0xf
	v_mov_b32_e32 v21, v20
	s_nop 1
	v_permlane16_swap_b32 v21, v20
	v_add_f32_e32 v20, v20, v21
	ds_bpermute_b32 v21, v59, v20
	s_and_saveexec_b64 s[2:3], s[38:39]
	s_cbranch_execz .LBB0_542
; __device__ __forceinline__ unsigned f2bf(float f) { unsigned u = __builtin_bit_cast(unsigned, f); return (u + 0x7fffu + ((u >> 16) & 1u)) >> 16; }
; __device__ __forceinline__ void gmlp_item(Frame& F, const Args& a, int l, int chunk, int g, const bf16* P, bf16* ACTA) {
;     ...
;             const float rstd = 1.0f / sqrtf(var + 1e-5f);
;             const f32x4 xm = myj ? x1 : x0;
;             if ((lane >> 5) == (g & 1)) {
;                 const int cl = 4 * (lane - mylo);
; #pragma unroll
;                 for (int j = 0; j < 4; ++j) Vt[(cl + j) * 136 + s] = (bf16)f2bf(xm[j] * rstd * lgv[j] + lbv[j]);
	v_cndmask_b32_e64 v12, v14, v12, s[0:1]
	s_waitcnt lgkmcnt(0)
	v_add_f32_e32 v14, v20, v21
	v_fmamk_f32 v14, v14, 0x3b000000, v215
	v_cndmask_b32_e64 v13, v15, v13, s[0:1]
	v_cmp_gt_f32_e32 vcc, s67, v14
	v_mul_f32_e32 v15, 0x4f800000, v14
	v_cndmask_b32_e64 v16, v18, v16, s[0:1]
	v_cndmask_b32_e32 v14, v14, v15, vcc
	v_sqrt_f32_e32 v15, v14
	v_cndmask_b32_e64 v17, v19, v17, s[0:1]
	v_add_u32_e32 v18, -1, v15
	v_fma_f32 v19, -v18, v15, v14
	v_cmp_ge_f32_e64 s[4:5], 0, v19
	v_add_u32_e32 v19, 1, v15
	s_nop 0
	v_cndmask_b32_e64 v18, v15, v18, s[4:5]
	v_fma_f32 v15, -v19, v15, v14
	v_cmp_lt_f32_e64 s[4:5], 0, v15
	s_nop 1
	v_cndmask_b32_e64 v15, v18, v19, s[4:5]
	v_mul_f32_e32 v18, 0x37800000, v15
	v_cndmask_b32_e32 v15, v15, v18, vcc
	v_cmp_class_f32_e32 vcc, v14, v213
	s_nop 1
	v_cndmask_b32_e32 v14, v15, v14, vcc
	v_div_scale_f32 v15, s[4:5], v14, v14, 1.0
	v_rcp_f32_e32 v18, v15
	s_nop 0
	v_fma_f32 v19, -v15, v18, 1.0
	v_fmac_f32_e32 v18, v19, v18
	v_div_scale_f32 v19, vcc, 1.0, v14, 1.0
	v_mul_f32_e32 v20, v19, v18
	v_fma_f32 v21, -v15, v20, v19
	v_fmac_f32_e32 v20, v21, v18
	v_fma_f32 v15, -v15, v20, v19
	v_div_fmas_f32 v15, v15, v18, v20
	v_div_fixup_f32 v14, v15, v14, 1.0
	v_mul_f32_e32 v12, v12, v14
	v_fma_f32 v12, v2, v12, v6
	v_bfe_u32 v15, v12, 16, 1
	v_add3_u32 v12, v12, v15, s7
	ds_write_b16_d16_hi v47, v12 offset:14
	v_mul_f32_e32 v12, v13, v14
	v_fma_f32 v12, v3, v12, v7
	v_bfe_u32 v13, v12, 16, 1
	v_add3_u32 v12, v12, v13, s7
	ds_write_b16_d16_hi v47, v12 offset:286
	v_mul_f32_e32 v12, v16, v14
	v_fma_f32 v12, v4, v12, v8
	v_bfe_u32 v13, v12, 16, 1
	v_add3_u32 v12, v12, v13, s7
	ds_write_b16_d16_hi v47, v12 offset:558
	v_mul_f32_e32 v12, v17, v14
	v_fma_f32 v12, v5, v12, v9
	v_bfe_u32 v13, v12, 16, 1
	v_add3_u32 v12, v12, v13, s7
	ds_write_b16_d16_hi v47, v12 offset:830
	s_branch .LBB0_542
